# attention MODE0 steady loop: back edge and ring/selection bookkeeping rotated in front of the step barrier; vacuous lgkmcnt waits and m0 save/restore dropped
# speedup vs baseline: 1.0437x; 1.0053x over previous
.LBB0_792:
	s_xor_b64 s[10:11], s[0:1], -1
	s_lshr_b32 s0, s8, 3
	s_mov_b32 s49, s7
	s_mov_b32 s50, s6
	s_add_u32 s28, s50, 0x26300000
	s_addc_u32 s29, s49, 0
	s_bfe_i32 s1, s0, 0x80000
	s_bfe_u32 s1, s1, 0x4000b
	s_add_i32 s1, s0, s1
	s_bfe_i32 s4, s1, 0x80000
	s_sext_i32_i16 s4, s4
	s_lshr_b32 s4, s4, 4
	s_and_b32 s1, s1, 0xf0
	s_sub_i32 s0, s0, s1
	s_bfe_i64 s[16:17], s[4:5], 0x100000
	s_add_u32 s34, s50, 0x23100400
	s_addc_u32 s35, s49, 0
	s_waitcnt lgkmcnt(0)
	v_mov_b32_e32 v52, v0
	s_add_u32 s30, s50, 0x23100600
	s_sext_i32_i8 s39, s0
	v_readfirstlane_b32 s22, v52
	s_addc_u32 s31, s49, 0
	s_ashr_i32 s44, s22, 6
	s_lshl_b64 s[0:1], s[16:17], 13
	s_lshl_b32 s64, s51, 8
	s_add_u32 s40, s0, s64
	s_addc_u32 s41, s1, 0
	s_lshl_b32 s0, s44, 5
	s_ashr_i32 s1, s0, 31
	s_add_u32 s20, s40, s0
	s_addc_u32 s21, s41, s1
	s_lshl_b32 s8, s39, 6
	s_lshl_b64 s[18:19], s[20:21], 10
	s_ashr_i32 s9, s8, 31
	s_ashr_i32 s5, s39, 2
	s_lshl_b64 s[12:13], s[16:17], 24
	s_add_u32 s23, s34, s12
	s_addc_u32 s25, s35, s13
	s_lshl_b32 s14, s5, 6
	s_ashr_i32 s15, s14, 31
	s_lshl_b64 s[14:15], s[14:15], 1
	s_add_u32 s24, s23, s14
	s_addc_u32 s25, s25, s15
	s_add_u32 s12, s30, s12
	v_and_b32_e32 v1, 63, v52
	s_addc_u32 s13, s31, s13
	s_add_u32 s14, s12, s14
	v_lshlrev_b32_e32 v2, 11, v1
	s_addc_u32 s15, s13, s15
	s_waitcnt vmcnt(0)
	v_lshl_add_u64 v[4:5], s[24:25], 0, v[2:3]
	s_lshl_b32 s23, s44, 4
	v_bfe_u32 v2, v52, 2, 4
	s_lshl_b32 s12, s44, 3
	v_and_or_b32 v210, s23, 48, v2
	s_ashr_i32 s13, s12, 31
	v_lshlrev_b32_e32 v2, 11, v210
	v_lshl_add_u64 v[188:189], s[12:13], 1, v[4:5]
	v_lshl_add_u64 v[4:5], s[14:15], 0, v[2:3]
	s_ashr_i32 s14, s22, 3
	s_andn2_b32 s14, s14, 31
	s_ashr_i32 s15, s14, 31
	s_lshl_b32 s45, s44, 10
	v_lshlrev_b32_e32 v212, 3, v52
	s_cmp_lg_u32 0, -1
	v_and_b32_e32 v211, 24, v212
	s_cselect_b32 s23, 0, 0
	v_lshl_add_u64 v[4:5], s[14:15], 1, v[4:5]
	v_lshlrev_b32_e32 v2, 1, v211
	s_add_i32 s46, s45, s23
	v_and_b32_e32 v208, 31, v52
	v_bfe_u32 v209, v52, 5, 1
	v_lshl_add_u64 v[84:85], v[4:5], 0, v[2:3]
	s_andn2_b64 vcc, exec, s[10:11]
	s_add_i32 s47, s46, 0x6000
	s_cbranch_vccnz .LBB0_794
	s_lshl_b64 s[10:11], s[18:19], 1
	s_add_u32 s23, s28, s10
	s_addc_u32 s24, s29, s11
	s_lshl_b64 s[10:11], s[8:9], 1
	s_add_u32 s10, s23, s10
	s_addc_u32 s11, s24, s11
	s_mov_b32 m0, s46
	s_nop 0
	global_load_lds_dwordx4 v[188:189], off
	s_cmp_lg_u32 0, -1
	s_mov_b32 m0, s47
	s_nop 0
	global_load_lds_dwordx4 v[84:85], off
	s_mov_b64 s[24:25], 0x20000
	s_cselect_b32 s23, 0, 0
	v_lshl_add_u64 v[4:5], v[188:189], 0, s[24:25]
	s_add_i32 s23, s23, s45
	s_addk_i32 s23, 0x2000
	s_mov_b32 m0, s23
	s_nop 0
	global_load_lds_dwordx4 v[4:5], off
	v_lshlrev_b32_e32 v4, 11, v208
	v_lshl_or_b32 v4, v209, 4, v4
	global_load_dwordx4 v[116:119], v4, s[10:11]
	global_load_dwordx4 v[120:123], v4, s[10:11] offset:32
	global_load_dwordx4 v[124:127], v4, s[10:11] offset:64
	global_load_dwordx4 v[128:131], v4, s[10:11] offset:96
.LBB0_794:
	s_sext_i32_i8 s4, s4
	s_lshl_b32 s4, s4, 2
	s_add_i32 s4, s5, s4
	s_ashr_i32 s5, s4, 31
	s_lshl_b64 s[4:5], s[4:5], 17
	s_add_u32 s10, s50, s4
	s_addc_u32 s11, s49, s5
	s_lshl_b64 s[4:5], s[64:65], 4
	s_add_u32 s10, s10, s4
	s_addc_u32 s11, s11, s5
	s_lshl_b64 s[4:5], s[0:1], 4
	v_lshlrev_b32_e32 v4, 10, v209
	s_waitcnt vmcnt(0)
	v_lshlrev_b32_e32 v36, 4, v208
	s_add_u32 s4, s10, s4
	v_add3_u32 v218, 0, v4, v36
	v_mov_b32_e32 v4, v3
	s_addc_u32 s5, s11, s5
	v_mov_b32_e32 v37, v3
	v_lshl_add_u64 v[36:37], s[4:5], 0, v[36:37]
	v_mov_b32_e32 v18, v4
	v_mov_b32_e32 v19, v4
	s_mov_b32 s1, 0x2b300000
	v_mov_b32_e32 v5, v4
	v_mov_b32_e32 v6, v4
	v_mov_b32_e32 v7, v4
	v_mov_b32_e32 v8, v4
	v_mov_b32_e32 v9, v4
	v_mov_b32_e32 v10, v4
	v_mov_b32_e32 v11, v4
	v_mov_b32_e32 v12, v4
	v_mov_b32_e32 v13, v4
	v_mov_b32_e32 v14, v4
	v_mov_b32_e32 v15, v4
	v_mov_b32_e32 v16, v4
	v_mov_b32_e32 v17, v4
	v_mov_b64_e32 v[34:35], v[18:19]
	v_add_co_u32_e32 v36, vcc, s1, v36
	v_mov_b64_e32 v[32:33], v[16:17]
	v_mov_b64_e32 v[30:31], v[14:15]
	v_mov_b64_e32 v[28:29], v[12:13]
	v_mov_b64_e32 v[26:27], v[10:11]
	v_mov_b64_e32 v[24:25], v[8:9]
	v_mov_b64_e32 v[22:23], v[6:7]
	v_mov_b64_e32 v[20:21], v[4:5]
	v_addc_co_u32_e32 v37, vcc, 0, v37, vcc
	global_load_dwordx4 v[132:135], v[36:37], off
	s_cmp_lg_u32 0, -1
	s_cselect_b32 s1, 0, 0
	s_add_i32 s1, s1, s45
	v_lshl_add_u64 v[36:37], v[188:189], 0, s[80:81]
	s_addk_i32 s1, 0x4000
	s_mov_b32 m0, s1
	s_nop 0
	global_load_lds_dwordx4 v[36:37], off
	s_waitcnt vmcnt(3) lgkmcnt(0)
	s_barrier
	ds_read_b128 v[54:57], v218
	s_waitcnt lgkmcnt(0)
	v_mfma_f32_32x32x16_bf16 v[36:51], v[54:57], v[116:119], v[20:35]
	ds_read_b128 v[54:57], v218 offset:512
	s_cmp_lg_u32 s51, 0
	s_cselect_b64 s[4:5], -1, 0
	v_or_b32_e32 v216, s0, v208
	s_and_b64 vcc, exec, s[4:5]
	v_lshlrev_b32_e32 v215, 2, v209
	s_waitcnt lgkmcnt(0)
	v_mfma_f32_32x32x16_bf16 v[20:35], v[54:57], v[116:119], v[20:35]
	ds_read_b128 v[54:57], v218 offset:2048
	s_waitcnt lgkmcnt(0)
	v_mfma_f32_32x32x16_bf16 v[36:51], v[54:57], v[120:123], v[36:51]
	ds_read_b128 v[54:57], v218 offset:2560
	s_waitcnt lgkmcnt(0)
	v_mfma_f32_32x32x16_bf16 v[20:35], v[54:57], v[120:123], v[20:35]
	ds_read_b128 v[54:57], v218 offset:4096
	s_waitcnt lgkmcnt(0)
	v_mfma_f32_32x32x16_bf16 v[36:51], v[54:57], v[124:127], v[36:51]
	ds_read_b128 v[54:57], v218 offset:4608
	s_waitcnt lgkmcnt(0)
	v_mfma_f32_32x32x16_bf16 v[20:35], v[54:57], v[124:127], v[20:35]
	ds_read_b128 v[54:57], v218 offset:6144
	s_waitcnt lgkmcnt(0)
	v_mfma_f32_32x32x16_bf16 v[36:51], v[54:57], v[128:131], v[36:51]
	ds_read_b128 v[54:57], v218 offset:6656
	s_waitcnt lgkmcnt(0)
	v_mfma_f32_32x32x16_bf16 v[20:35], v[54:57], v[128:131], v[20:35]
	s_nop 15
	s_nop 7
	s_cbranch_vccnz .LBB0_796
	v_or_b32_e32 v54, 32, v215
	v_subrev_u32_e32 v53, s64, v215
	v_cmp_le_i32_e32 vcc, v54, v216
	s_nop 7
	v_cndmask_b32_e32 v20, v232, v20, vcc
	v_cmp_lt_i32_e32 vcc, v53, v216
	s_nop 1
	v_cndmask_b32_e32 v37, v232, v37, vcc
	v_cmp_le_i32_e32 vcc, v53, v216
	v_or_b32_e32 v53, 33, v215
	s_nop 0
	v_cndmask_b32_e32 v36, v232, v36, vcc
	v_cmp_le_i32_e32 vcc, v53, v216
	v_or_b32_e32 v53, 2, v215
	s_nop 0
	v_cndmask_b32_e32 v21, v232, v21, vcc
	v_cmp_le_i32_e32 vcc, v53, v216
	v_or_b32_e32 v53, 34, v215
	s_nop 0
	v_cndmask_b32_e32 v38, v232, v38, vcc
	v_cmp_le_i32_e32 vcc, v53, v216
	v_or_b32_e32 v53, 3, v215
	s_nop 0
	v_cndmask_b32_e32 v22, v232, v22, vcc
	v_cmp_le_i32_e32 vcc, v53, v216
	v_or_b32_e32 v53, 35, v215
	s_nop 0
	v_cndmask_b32_e32 v39, v232, v39, vcc
	v_cmp_le_i32_e32 vcc, v53, v216
	v_or_b32_e32 v53, 8, v215
	s_nop 0
	v_cndmask_b32_e32 v23, v232, v23, vcc
	v_cmp_le_i32_e32 vcc, v53, v216
	v_or_b32_e32 v53, 40, v215
	s_nop 0
	v_cndmask_b32_e32 v40, v232, v40, vcc
	v_cmp_le_i32_e32 vcc, v53, v216
	v_or_b32_e32 v53, 9, v215
	s_nop 0
	v_cndmask_b32_e32 v24, v232, v24, vcc
	v_cmp_le_i32_e32 vcc, v53, v216
	v_or_b32_e32 v53, 41, v215
	s_nop 0
	v_cndmask_b32_e32 v41, v232, v41, vcc
	v_cmp_le_i32_e32 vcc, v53, v216
	v_or_b32_e32 v53, 10, v215
	s_nop 0
	v_cndmask_b32_e32 v25, v232, v25, vcc
	v_cmp_le_i32_e32 vcc, v53, v216
	v_or_b32_e32 v53, 42, v215
	s_nop 0
	v_cndmask_b32_e32 v42, v232, v42, vcc
	v_cmp_le_i32_e32 vcc, v53, v216
	v_or_b32_e32 v53, 11, v215
	s_nop 0
	v_cndmask_b32_e32 v26, v232, v26, vcc
	v_cmp_le_i32_e32 vcc, v53, v216
	v_or_b32_e32 v53, 43, v215
	s_nop 0
	v_cndmask_b32_e32 v43, v232, v43, vcc
	v_cmp_le_i32_e32 vcc, v53, v216
	v_or_b32_e32 v53, 16, v215
	s_nop 0
	v_cndmask_b32_e32 v27, v232, v27, vcc
	v_cmp_le_i32_e32 vcc, v53, v216
	v_or_b32_e32 v53, 48, v215
	s_nop 0
	v_cndmask_b32_e32 v44, v232, v44, vcc
	v_cmp_le_i32_e32 vcc, v53, v216
	v_or_b32_e32 v53, 17, v215
	s_nop 0
	v_cndmask_b32_e32 v28, v232, v28, vcc
	v_cmp_le_i32_e32 vcc, v53, v216
	v_or_b32_e32 v53, 49, v215
	s_nop 0
	v_cndmask_b32_e32 v45, v232, v45, vcc
	v_cmp_le_i32_e32 vcc, v53, v216
	v_or_b32_e32 v53, 18, v215
	s_nop 0
	v_cndmask_b32_e32 v29, v232, v29, vcc
	v_cmp_le_i32_e32 vcc, v53, v216
	v_or_b32_e32 v53, 50, v215
	s_nop 0
	v_cndmask_b32_e32 v46, v232, v46, vcc
	v_cmp_le_i32_e32 vcc, v53, v216
	v_or_b32_e32 v53, 19, v215
	s_nop 0
	v_cndmask_b32_e32 v30, v232, v30, vcc
	v_cmp_le_i32_e32 vcc, v53, v216
	v_or_b32_e32 v53, 51, v215
	s_nop 0
	v_cndmask_b32_e32 v47, v232, v47, vcc
	v_cmp_le_i32_e32 vcc, v53, v216
	v_or_b32_e32 v53, 24, v215
	s_nop 0
	v_cndmask_b32_e32 v31, v232, v31, vcc
	v_cmp_le_i32_e32 vcc, v53, v216
	v_or_b32_e32 v53, 56, v215
	s_nop 0
	v_cndmask_b32_e32 v48, v232, v48, vcc
	v_cmp_le_i32_e32 vcc, v53, v216
	v_or_b32_e32 v53, 25, v215
	s_nop 0
	v_cndmask_b32_e32 v32, v232, v32, vcc
	v_cmp_le_i32_e32 vcc, v53, v216
	v_or_b32_e32 v53, 57, v215
	s_nop 0
	v_cndmask_b32_e32 v49, v232, v49, vcc
	v_cmp_le_i32_e32 vcc, v53, v216
	v_or_b32_e32 v53, 26, v215
	s_nop 0
	v_cndmask_b32_e32 v33, v232, v33, vcc
	v_cmp_le_i32_e32 vcc, v53, v216
	v_or_b32_e32 v53, 58, v215
	s_nop 0
	v_cndmask_b32_e32 v50, v232, v50, vcc
	v_cmp_le_i32_e32 vcc, v53, v216
	v_or_b32_e32 v53, 27, v215
	s_nop 0
	v_cndmask_b32_e32 v34, v232, v34, vcc
	v_cmp_le_i32_e32 vcc, v53, v216
	v_or_b32_e32 v53, 59, v215
	s_nop 0
	v_cndmask_b32_e32 v51, v232, v51, vcc
	v_cmp_le_i32_e32 vcc, v53, v216
	s_nop 1
	v_cndmask_b32_e32 v35, v232, v35, vcc
.LBB0_796:
	v_lshlrev_b32_e32 v53, 1, v52
	v_lshlrev_b32_e32 v52, 4, v52
	v_and_b32_e32 v214, 32, v53
	v_and_b32_e32 v52, 0xc0, v52
	v_lshl_or_b32 v213, v209, 8, v52
	v_add_u32_e32 v52, 0, v214
	v_add3_u32 v219, v52, v211, v213
	v_max3_f32 v52, v36, v37, v20
	v_max3_f32 v53, v38, v39, v21
	s_and_b32 s0, s22, 0x3fffffc0
	v_max3_f32 v52, v52, v22, v23
	v_max3_f32 v53, v53, v42, v43
	s_lshl_b32 s0, s0, 2
	v_max3_f32 v52, v52, v40, v41
	v_max3_f32 v53, v53, v26, v27
	s_add_i32 s1, s64, 0x100
	v_max3_f32 v52, v52, v24, v25
	v_max3_f32 v53, v53, v46, v47
	s_add_i32 s53, s0, 0
	v_max3_f32 v52, v52, v44, v45
	v_max3_f32 v53, v53, v30, v31
	s_lshr_b32 s48, s1, 6
	v_max3_f32 v52, v52, v28, v29
	v_max3_f32 v53, v53, v50, v51
	s_mov_b64 s[22:23], 0x60000
	v_max3_f32 v52, v52, v48, v49
	v_max3_f32 v53, v53, v34, v35
	s_cmp_lg_u32 0, -1
	v_max3_f32 v52, v52, v32, v33
	s_mov_b64 s[10:11], 0x20000
	v_max_f32_e32 v52, v52, v53
	v_lshl_add_u64 v[190:191], v[84:85], 0, s[10:11]
	v_mov_b32_e32 v53, v52
	s_nop 1
	v_permlane32_swap_b32_e32 v52, v53
	v_max_f32_e32 v52, v52, v53
	s_mov_b32 s0, 1
	v_max_f32_e32 v52, v52, v228
	s_mov_b32 s24, 0
	v_add_f32_e32 v217, v3, v52
	v_sub_f32_e32 v53, v36, v52
	v_sub_f32_e32 v54, v37, v52
	v_sub_f32_e32 v55, v38, v52
	v_sub_f32_e32 v56, v39, v52
	v_sub_f32_e32 v57, v40, v52
	s_nop 0
	v_xor_b32_e32 v36, 0x80000000, v217
	v_sub_f32_e32 v58, v41, v52
	v_sub_f32_e32 v59, v42, v52
	v_sub_f32_e32 v60, v43, v52
	v_sub_f32_e32 v61, v44, v52
	v_sub_f32_e32 v62, v45, v52
	v_sub_f32_e32 v63, v46, v52
	v_sub_f32_e32 v64, v47, v52
	v_sub_f32_e32 v65, v48, v52
	v_sub_f32_e32 v66, v49, v52
	v_sub_f32_e32 v67, v50, v52
	v_sub_f32_e32 v83, v51, v52
	v_mov_b32_e32 v37, v36
	v_mov_b32_e32 v38, v36
	v_mov_b32_e32 v39, v36
	v_mov_b32_e32 v40, v36
	v_mov_b32_e32 v41, v36
	v_mov_b32_e32 v42, v36
	v_mov_b32_e32 v43, v36
	v_mov_b32_e32 v44, v36
	v_mov_b32_e32 v45, v36
	v_mov_b32_e32 v46, v36
	v_mov_b32_e32 v47, v36
	v_mov_b32_e32 v48, v36
	v_mov_b32_e32 v49, v36
	v_mov_b32_e32 v50, v36
	v_mov_b32_e32 v51, v36
	v_sub_f32_e32 v20, v20, v52
	v_sub_f32_e32 v21, v21, v52
	s_waitcnt vmcnt(0) lgkmcnt(0)
	s_barrier
	v_sub_f32_e32 v22, v22, v52
	v_sub_f32_e32 v23, v23, v52
	v_sub_f32_e32 v24, v24, v52
	v_sub_f32_e32 v25, v25, v52
	v_sub_f32_e32 v26, v26, v52
	v_sub_f32_e32 v27, v27, v52
	v_sub_f32_e32 v28, v28, v52
	v_sub_f32_e32 v29, v29, v52
	v_sub_f32_e32 v30, v30, v52
	v_sub_f32_e32 v31, v31, v52
	v_sub_f32_e32 v32, v32, v52
	v_sub_f32_e32 v33, v33, v52
	v_sub_f32_e32 v34, v34, v52
	v_sub_f32_e32 v35, v35, v52
	v_exp_f32_e32 v68, v53
	v_exp_f32_e32 v52, v20
	v_exp_f32_e32 v53, v21
	v_lshl_add_u64 v[20:21], v[188:189], 0, s[22:23]
	s_mov_b32 m0, s46
	s_nop 0
	global_load_lds_dwordx4 v[20:21], off
	s_cselect_b32 s1, 0, 0
	s_add_i32 s1, s1, s45
	s_add_i32 s1, s1, 0x8000
	s_mov_b32 m0, s1
	s_nop 0
	global_load_lds_dwordx4 v[190:191], off
	ds_read_b128 v[180:183], v218 offset:8192
	ds_read_b128 v[176:179], v218 offset:8704
	ds_read_b128 v[172:175], v218 offset:10240
	ds_read_b128 v[168:171], v218 offset:10752
	ds_read_b128 v[164:167], v218 offset:12288
	ds_read_b128 v[160:163], v218 offset:12800
	ds_read_b128 v[156:159], v218 offset:14336
	ds_read_b128 v[152:155], v218 offset:14848
	v_exp_f32_e32 v69, v54
	v_exp_f32_e32 v70, v55
	v_exp_f32_e32 v71, v56
	v_exp_f32_e32 v72, v57
	v_exp_f32_e32 v73, v58
	v_exp_f32_e32 v74, v59
	v_exp_f32_e32 v75, v60
	v_exp_f32_e32 v76, v61
	v_exp_f32_e32 v77, v62
	v_exp_f32_e32 v78, v63
	v_exp_f32_e32 v79, v64
	v_exp_f32_e32 v80, v65
	v_exp_f32_e32 v81, v66
	v_exp_f32_e32 v82, v67
	v_exp_f32_e32 v83, v83
	v_exp_f32_e32 v54, v22
	v_exp_f32_e32 v55, v23
	v_exp_f32_e32 v56, v24
	v_exp_f32_e32 v57, v25
	v_exp_f32_e32 v58, v26
	v_exp_f32_e32 v59, v27
	v_exp_f32_e32 v60, v28
	v_exp_f32_e32 v61, v29
	v_exp_f32_e32 v62, v30
	v_exp_f32_e32 v63, v31
	v_exp_f32_e32 v64, v32
	v_exp_f32_e32 v65, v33
	v_exp_f32_e32 v66, v34
	v_exp_f32_e32 v67, v35
	s_waitcnt vmcnt(2) lgkmcnt(0)
	s_barrier
	s_andn2_b64 vcc, exec, s[4:5]
	v_cmp_gt_u32_e64 s[4:5], 32, v1
	s_cbranch_vccnz .LBB0_812
	v_lshlrev_b32_e32 v20, 4, v209
	s_mov_b64 s[10:11], 0xa0000
	v_add_u32_e32 v203, s53, v20
	v_mov_b64_e32 v[34:35], v[18:19]
	s_add_i32 s1, s48, -5
	v_lshl_add_u32 v202, v208, 2, s53
	v_lshl_add_u64 v[192:193], v[84:85], 0, s[22:23]
	v_lshl_add_u64 v[194:195], v[188:189], 0, s[10:11]
	s_movk_i32 s24, 0x4000
	s_movk_i32 s25, 0x2000
	s_mov_b32 s10, 0
	v_mov_b32_e32 v220, 0
	v_mov_b64_e32 v[32:33], v[16:17]
	v_mov_b64_e32 v[30:31], v[14:15]
	v_mov_b64_e32 v[28:29], v[12:13]
	v_mov_b64_e32 v[26:27], v[10:11]
	v_mov_b64_e32 v[24:25], v[8:9]
	v_mov_b64_e32 v[22:23], v[6:7]
	v_mov_b64_e32 v[20:21], v[4:5]
	s_branch .LBB0_798

.LBB0_798:
	v_bfe_i32 v196, v132, 0, 1
	v_add_u32_e32 v197, s10, v219
	ds_read_b64_tr_b16 v[184:185], v197 offset:24576
	ds_read_b64_tr_b16 v[186:187], v197 offset:25088
	v_mfma_f32_32x32x16_bf16 v[100:115], v[180:183], v[116:119], v[36:51]
	v_add_f32_e32 v84, v68, v69
	v_add_f32_e32 v84, v70, v84
	v_add_f32_e32 v84, v71, v84
	v_cvt_pk_bf16_f32 v68, v68, v69
	v_add_f32_e32 v84, v72, v84
	v_and_b32_e32 v148, v68, v196
	v_cvt_pk_bf16_f32 v68, v70, v71
	v_add_f32_e32 v84, v73, v84
	v_and_b32_e32 v149, v68, v196
	ds_read_b64_tr_b16 v[180:181], v197 offset:28672
	ds_read_b64_tr_b16 v[182:183], v197 offset:29184
	v_add_f32_e32 v68, v74, v84
	v_mfma_f32_32x32x16_bf16 v[84:99], v[176:179], v[116:119], v[36:51]
	v_add_f32_e32 v68, v75, v68
	v_add_f32_e32 v68, v76, v68
	v_add_f32_e32 v136, v77, v68
	v_cvt_pk_bf16_f32 v68, v72, v73
	v_and_b32_e32 v150, v68, v196
	v_cvt_pk_bf16_f32 v68, v74, v75
	v_and_b32_e32 v151, v68, v196
	ds_read_b64_tr_b16 v[68:69], v197 offset:25600
	ds_read_b64_tr_b16 v[70:71], v197 offset:26112
	v_mfma_f32_32x32x16_bf16 v[100:115], v[172:175], v[120:123], v[100:115]
	v_add_f32_e32 v72, v78, v136
	v_add_f32_e32 v72, v79, v72
	v_add_f32_e32 v72, v80, v72
	v_add_f32_e32 v136, v81, v72
	v_cvt_pk_bf16_f32 v72, v76, v77
	v_and_b32_e32 v144, v72, v196
	v_cvt_pk_bf16_f32 v72, v78, v79
	v_and_b32_e32 v145, v72, v196
	ds_read_b64_tr_b16 v[72:73], v197 offset:29696
	ds_read_b64_tr_b16 v[74:75], v197 offset:30208
	v_mfma_f32_32x32x16_bf16 v[84:99], v[168:171], v[120:123], v[84:99]
	v_add_f32_e32 v76, v82, v136
	v_add_f32_e32 v76, v83, v76
	v_add_f32_e32 v76, v52, v76
	v_add_f32_e32 v136, v53, v76
	v_cvt_pk_bf16_f32 v76, v80, v81
	v_and_b32_e32 v146, v76, v196
	v_cvt_pk_bf16_f32 v76, v82, v83
	v_and_b32_e32 v147, v76, v196
	ds_read_b64_tr_b16 v[76:77], v197 offset:26624
	ds_read_b64_tr_b16 v[78:79], v197 offset:27136
	v_mfma_f32_32x32x16_bf16 v[100:115], v[164:167], v[124:127], v[100:115]
	v_add_f32_e32 v80, v54, v136
	v_add_f32_e32 v80, v55, v80
	v_cvt_pk_bf16_f32 v52, v52, v53
	v_add_f32_e32 v80, v56, v80
	v_and_b32_e32 v140, v52, v196
	v_cvt_pk_bf16_f32 v52, v54, v55
	v_add_f32_e32 v80, v57, v80
	v_and_b32_e32 v141, v52, v196
	ds_read_b64_tr_b16 v[52:53], v197 offset:30720
	ds_read_b64_tr_b16 v[54:55], v197 offset:31232
	v_mfma_f32_32x32x16_bf16 v[84:99], v[160:163], v[124:127], v[84:99]
	v_add_f32_e32 v80, v58, v80
	v_add_f32_e32 v80, v59, v80
	v_cvt_pk_bf16_f32 v56, v56, v57
	v_add_f32_e32 v80, v60, v80
	v_and_b32_e32 v142, v56, v196
	v_cvt_pk_bf16_f32 v56, v58, v59
	v_add_f32_e32 v80, v61, v80
	v_and_b32_e32 v143, v56, v196
	ds_read_b64_tr_b16 v[56:57], v197 offset:27648
	ds_read_b64_tr_b16 v[58:59], v197 offset:28160
	v_mfma_f32_32x32x16_bf16 v[100:115], v[156:159], v[128:131], v[100:115]
	v_add_f32_e32 v80, v62, v80
	v_add_f32_e32 v80, v63, v80
	v_cvt_pk_bf16_f32 v60, v60, v61
	v_add_f32_e32 v80, v64, v80
	v_and_b32_e32 v136, v60, v196
	v_cvt_pk_bf16_f32 v60, v62, v63
	v_add_f32_e32 v80, v65, v80
	v_and_b32_e32 v137, v60, v196
	ds_read_b64_tr_b16 v[60:61], v197 offset:31744
	ds_read_b64_tr_b16 v[62:63], v197 offset:32256
	v_mfma_f32_32x32x16_bf16 v[84:99], v[152:155], v[128:131], v[84:99]
	v_add_f32_e32 v80, v66, v80
	v_cvt_pk_bf16_f32 v64, v64, v65
	v_add_f32_e32 v80, v67, v80
	v_and_b32_e32 v138, v64, v196
	v_cvt_pk_bf16_f32 v64, v66, v67
	v_and_b32_e32 v139, v64, v196
	s_mov_b32 s22, 0xfffe0000
	s_mov_b32 s23, -1
	v_lshl_add_u64 v[64:65], v[194:195], 0, s[22:23]
	s_add_i32 s10, s25, s46
	s_mov_b32 m0, s10
	s_nop 0
	global_load_lds_dwordx4 v[64:65], off
	v_lshl_add_u64 v[64:65], v[192:193], 0, s[22:23]
	s_add_i32 s10, s24, s47
	s_mov_b32 m0, s10
	s_nop 0
	global_load_lds_dwordx4 v[64:65], off
	v_and_b32_e32 v66, v80, v196
	v_add_f32_e32 v204, v220, v66
.LBB0_799:
	s_waitcnt lgkmcnt(14)
	v_mfma_f32_32x32x16_bf16 v[20:35], v[148:151], v[184:187], v[20:35]
	v_exp_f32_e32 v100, v100
	v_exp_f32_e32 v101, v101
	v_exp_f32_e32 v102, v102
	v_exp_f32_e32 v103, v103
	s_waitcnt lgkmcnt(12)
	v_mfma_f32_32x32x16_bf16 v[4:19], v[148:151], v[180:183], v[4:19]
	v_exp_f32_e32 v104, v104
	v_exp_f32_e32 v105, v105
	v_exp_f32_e32 v106, v106
	v_exp_f32_e32 v107, v107
	v_add_u32_e32 v80, s24, v218
	ds_read_b128 v[64:67], v80
	ds_read_b128 v[180:183], v80 offset:512
	s_waitcnt lgkmcnt(12)
	v_mfma_f32_32x32x16_bf16 v[20:35], v[144:147], v[68:71], v[20:35]
	v_exp_f32_e32 v108, v108
	v_exp_f32_e32 v109, v109
	v_exp_f32_e32 v110, v110
	v_exp_f32_e32 v111, v111
	ds_read_b128 v[184:187], v80 offset:2048
	ds_read_b128 v[176:179], v80 offset:2560
	s_waitcnt lgkmcnt(12)
	v_mfma_f32_32x32x16_bf16 v[4:19], v[144:147], v[72:75], v[4:19]
	v_exp_f32_e32 v112, v112
	v_exp_f32_e32 v113, v113
	v_exp_f32_e32 v114, v114
	v_exp_f32_e32 v115, v115
	ds_read_b128 v[172:175], v80 offset:4096
	ds_read_b128 v[168:171], v80 offset:4608
	s_waitcnt lgkmcnt(12)
	v_mfma_f32_32x32x16_bf16 v[20:35], v[140:143], v[76:79], v[20:35]
	v_exp_f32_e32 v84, v84
	v_exp_f32_e32 v85, v85
	v_exp_f32_e32 v86, v86
	v_exp_f32_e32 v87, v87
	ds_read_b128 v[164:167], v80 offset:6144
	ds_read_b128 v[160:163], v80 offset:6656
	s_waitcnt lgkmcnt(12)
	v_mfma_f32_32x32x16_bf16 v[4:19], v[140:143], v[52:55], v[4:19]
	v_exp_f32_e32 v88, v88
	v_exp_f32_e32 v89, v89
	v_exp_f32_e32 v90, v90
	v_exp_f32_e32 v91, v91
	s_waitcnt lgkmcnt(10)
	v_mfma_f32_32x32x16_bf16 v[20:35], v[136:139], v[56:59], v[20:35]
	v_exp_f32_e32 v92, v92
	v_exp_f32_e32 v93, v93
	v_exp_f32_e32 v94, v94
	v_exp_f32_e32 v95, v95
	s_waitcnt lgkmcnt(8)
	v_mfma_f32_32x32x16_bf16 v[4:19], v[136:139], v[60:63], v[4:19]
	v_exp_f32_e32 v96, v96
	v_exp_f32_e32 v97, v97
	v_exp_f32_e32 v98, v98
	v_exp_f32_e32 v99, v99
	s_add_i32 s10, s24, 0x2000
	s_cmpk_lg_i32 s24, 0x4000
	v_alignbit_b32 v132, v133, v132, 1
	s_cselect_b32 s54, s10, 0
	s_waitcnt vmcnt(2) lgkmcnt(0)
	s_barrier
.LBB0_801:
	v_bfe_i32 v196, v132, 0, 1
	v_add_u32_e32 v197, s25, v219
	ds_read_b64_tr_b16 v[152:153], v197 offset:24576
	ds_read_b64_tr_b16 v[154:155], v197 offset:25088
	v_mfma_f32_32x32x16_bf16 v[68:83], v[64:67], v[116:119], v[36:51]
	v_add_f32_e32 v52, v100, v101
	v_add_f32_e32 v52, v102, v52
	v_add_f32_e32 v52, v103, v52
	v_cvt_pk_bf16_f32 v53, v100, v101
	v_add_f32_e32 v52, v104, v52
	v_and_b32_e32 v148, v53, v196
	v_cvt_pk_bf16_f32 v53, v102, v103
	v_add_f32_e32 v52, v105, v52
	v_and_b32_e32 v149, v53, v196
	ds_read_b64_tr_b16 v[156:157], v197 offset:28672
	ds_read_b64_tr_b16 v[158:159], v197 offset:29184
	v_add_f32_e32 v52, v106, v52
	v_add_f32_e32 v52, v107, v52
	v_add_f32_e32 v52, v108, v52
	v_add_f32_e32 v136, v109, v52
	v_mfma_f32_32x32x16_bf16 v[52:67], v[180:183], v[116:119], v[36:51]
	v_cvt_pk_bf16_f32 v100, v104, v105
	v_and_b32_e32 v150, v100, v196
	v_cvt_pk_bf16_f32 v100, v106, v107
	v_and_b32_e32 v151, v100, v196
	ds_read_b64_tr_b16 v[100:101], v197 offset:25600
	ds_read_b64_tr_b16 v[102:103], v197 offset:26112
	v_mfma_f32_32x32x16_bf16 v[68:83], v[184:187], v[120:123], v[68:83]
	v_add_f32_e32 v104, v110, v136
	v_add_f32_e32 v104, v111, v104
	v_add_f32_e32 v104, v112, v104
	v_add_f32_e32 v136, v113, v104
	v_cvt_pk_bf16_f32 v104, v108, v109
	v_and_b32_e32 v144, v104, v196
	v_cvt_pk_bf16_f32 v104, v110, v111
	v_and_b32_e32 v145, v104, v196
	ds_read_b64_tr_b16 v[104:105], v197 offset:29696
	ds_read_b64_tr_b16 v[106:107], v197 offset:30208
	v_mfma_f32_32x32x16_bf16 v[52:67], v[176:179], v[120:123], v[52:67]
	v_add_f32_e32 v108, v114, v136
	v_add_f32_e32 v108, v115, v108
	v_add_f32_e32 v108, v84, v108
	v_add_f32_e32 v136, v85, v108
	v_cvt_pk_bf16_f32 v108, v112, v113
	v_and_b32_e32 v146, v108, v196
	v_cvt_pk_bf16_f32 v108, v114, v115
	v_and_b32_e32 v147, v108, v196
	ds_read_b64_tr_b16 v[108:109], v197 offset:26624
	ds_read_b64_tr_b16 v[110:111], v197 offset:27136
	v_mfma_f32_32x32x16_bf16 v[68:83], v[172:175], v[124:127], v[68:83]
	v_add_f32_e32 v112, v86, v136
	v_add_f32_e32 v112, v87, v112
	v_cvt_pk_bf16_f32 v84, v84, v85
	v_add_f32_e32 v112, v88, v112
	v_and_b32_e32 v140, v84, v196
	v_cvt_pk_bf16_f32 v84, v86, v87
	v_add_f32_e32 v112, v89, v112
	v_and_b32_e32 v141, v84, v196
	ds_read_b64_tr_b16 v[84:85], v197 offset:30720
	ds_read_b64_tr_b16 v[86:87], v197 offset:31232
	v_mfma_f32_32x32x16_bf16 v[52:67], v[168:171], v[124:127], v[52:67]
	v_add_f32_e32 v112, v90, v112
	v_add_f32_e32 v112, v91, v112
	v_cvt_pk_bf16_f32 v88, v88, v89
	v_add_f32_e32 v112, v92, v112
	v_and_b32_e32 v142, v88, v196
	v_cvt_pk_bf16_f32 v88, v90, v91
	v_add_f32_e32 v112, v93, v112
	v_and_b32_e32 v143, v88, v196
	ds_read_b64_tr_b16 v[88:89], v197 offset:27648
	ds_read_b64_tr_b16 v[90:91], v197 offset:28160
	v_mfma_f32_32x32x16_bf16 v[68:83], v[164:167], v[128:131], v[68:83]
	v_add_f32_e32 v112, v94, v112
	v_add_f32_e32 v112, v95, v112
	v_cvt_pk_bf16_f32 v92, v92, v93
	v_add_f32_e32 v112, v96, v112
	v_and_b32_e32 v136, v92, v196
	v_cvt_pk_bf16_f32 v92, v94, v95
	v_add_f32_e32 v112, v97, v112
	v_and_b32_e32 v137, v92, v196
	ds_read_b64_tr_b16 v[92:93], v197 offset:31744
	ds_read_b64_tr_b16 v[94:95], v197 offset:32256
	v_mfma_f32_32x32x16_bf16 v[52:67], v[160:163], v[128:131], v[52:67]
	v_add_f32_e32 v112, v98, v112
	v_cvt_pk_bf16_f32 v96, v96, v97
	v_add_f32_e32 v112, v99, v112
	v_and_b32_e32 v138, v96, v196
	v_cvt_pk_bf16_f32 v96, v98, v99
	v_and_b32_e32 v139, v96, v196
	v_and_b32_e32 v96, v112, v196
	v_add_f32_e32 v220, v204, v96
	s_add_i32 s10, s24, s46
	s_mov_b32 m0, s10
	s_nop 0
	global_load_lds_dwordx4 v[194:195], off
	s_add_i32 s10, s54, s47
	s_mov_b32 m0, s10
	s_nop 0
	global_load_lds_dwordx4 v[192:193], off
.LBB0_802:
	s_waitcnt lgkmcnt(14)
	v_mfma_f32_32x32x16_bf16 v[20:35], v[148:151], v[152:155], v[20:35]
	v_exp_f32_e32 v68, v68
	v_exp_f32_e32 v69, v69
	v_exp_f32_e32 v70, v70
	v_exp_f32_e32 v71, v71
	s_waitcnt lgkmcnt(12)
	v_mfma_f32_32x32x16_bf16 v[4:19], v[148:151], v[156:159], v[4:19]
	v_exp_f32_e32 v72, v72
	v_exp_f32_e32 v73, v73
	v_exp_f32_e32 v74, v74
	v_exp_f32_e32 v75, v75
	v_add_u32_e32 v96, s54, v218
	ds_read_b128 v[180:183], v96
	ds_read_b128 v[176:179], v96 offset:512
	s_waitcnt lgkmcnt(12)
	v_mfma_f32_32x32x16_bf16 v[20:35], v[144:147], v[100:103], v[20:35]
	v_exp_f32_e32 v76, v76
	v_exp_f32_e32 v77, v77
	v_exp_f32_e32 v78, v78
	v_exp_f32_e32 v79, v79
	ds_read_b128 v[172:175], v96 offset:2048
	ds_read_b128 v[168:171], v96 offset:2560
	s_waitcnt lgkmcnt(12)
	v_mfma_f32_32x32x16_bf16 v[4:19], v[144:147], v[104:107], v[4:19]
	v_exp_f32_e32 v80, v80
	v_exp_f32_e32 v81, v81
	v_exp_f32_e32 v82, v82
	v_exp_f32_e32 v83, v83
	ds_read_b128 v[164:167], v96 offset:4096
	ds_read_b128 v[160:163], v96 offset:4608
	s_waitcnt lgkmcnt(12)
	v_mfma_f32_32x32x16_bf16 v[20:35], v[140:143], v[108:111], v[20:35]
	v_exp_f32_e32 v52, v52
	v_exp_f32_e32 v53, v53
	v_exp_f32_e32 v54, v54
	v_exp_f32_e32 v55, v55
	ds_read_b128 v[156:159], v96 offset:6144
	ds_read_b128 v[152:155], v96 offset:6656
	s_waitcnt lgkmcnt(12)
	v_mfma_f32_32x32x16_bf16 v[4:19], v[140:143], v[84:87], v[4:19]
	v_exp_f32_e32 v56, v56
	v_exp_f32_e32 v57, v57
	v_exp_f32_e32 v58, v58
	v_exp_f32_e32 v59, v59
	s_waitcnt lgkmcnt(10)
	v_mfma_f32_32x32x16_bf16 v[20:35], v[136:139], v[88:91], v[20:35]
	v_exp_f32_e32 v60, v60
	v_exp_f32_e32 v61, v61
	v_exp_f32_e32 v62, v62
	v_exp_f32_e32 v63, v63
	s_waitcnt lgkmcnt(8)
	v_mfma_f32_32x32x16_bf16 v[4:19], v[136:139], v[92:95], v[4:19]
	v_exp_f32_e32 v64, v64
	v_exp_f32_e32 v65, v65
	v_exp_f32_e32 v66, v66
	v_exp_f32_e32 v67, v67
	s_add_i32 s0, s0, 2
	s_add_i32 s10, s54, 0x2000
	v_alignbit_b32 v84, v135, v134, 1
	v_alignbit_b32 v85, v134, v133, 1
	v_lshrrev_b32_e32 v86, 1, v135
	s_cmpk_lg_i32 s54, 0x4000
	v_alignbit_b32 v132, v85, v132, 1
	v_alignbit_b32 v133, v84, v85, 1
	v_alignbit_b32 v134, v86, v84, 1
	v_lshrrev_b32_e32 v135, 2, v135
	s_cselect_b32 s42, s10, 0
	v_lshl_add_u64 v[192:193], v[192:193], 0, s[80:81]
	s_cmp_ge_i32 s0, s1
	v_lshl_add_u64 v[194:195], v[194:195], 0, s[80:81]
	s_cbranch_scc1 .Lattn0_exit
	s_mov_b32 s10, s24
	s_mov_b32 s25, s54
	s_mov_b32 s24, s42
	s_branch .Lattn0_head
.Lattn0_exit:
	s_waitcnt vmcnt(2) lgkmcnt(0)
	s_barrier
	s_branch .LBB0_813
.LBB0_804:
.LBB0_812:
	v_mov_b64_e32 v[34:35], v[18:19]
	s_movk_i32 s42, 0x4000
	s_movk_i32 s54, 0x2000
	v_mov_b32_e32 v220, 0
	v_mov_b64_e32 v[32:33], v[16:17]
	v_mov_b64_e32 v[30:31], v[14:15]
	v_mov_b64_e32 v[28:29], v[12:13]
	v_mov_b64_e32 v[26:27], v[10:11]
	v_mov_b64_e32 v[24:25], v[8:9]
	v_mov_b64_e32 v[22:23], v[6:7]
	v_mov_b64_e32 v[20:21], v[4:5]

.LBB0_815:
	v_bfe_i32 v188, v132, 0, 1
	v_add_u32_e32 v189, s24, v219
	ds_read_b64_tr_b16 v[184:185], v189 offset:24576
	ds_read_b64_tr_b16 v[186:187], v189 offset:25088
	v_mfma_f32_32x32x16_bf16 v[100:115], v[180:183], v[116:119], v[36:51]
	v_add_f32_e32 v84, v68, v69
	v_add_f32_e32 v84, v70, v84
	v_add_f32_e32 v84, v71, v84
	v_cvt_pk_bf16_f32 v68, v68, v69
	v_add_f32_e32 v84, v72, v84
	v_and_b32_e32 v148, v68, v188
	v_cvt_pk_bf16_f32 v68, v70, v71
	v_add_f32_e32 v84, v73, v84
	v_and_b32_e32 v149, v68, v188
	ds_read_b64_tr_b16 v[180:181], v189 offset:28672
	ds_read_b64_tr_b16 v[182:183], v189 offset:29184
	v_add_f32_e32 v68, v74, v84
	v_mfma_f32_32x32x16_bf16 v[84:99], v[176:179], v[116:119], v[36:51]
	v_add_f32_e32 v68, v75, v68
	v_add_f32_e32 v68, v76, v68
	v_add_f32_e32 v136, v77, v68
	v_cvt_pk_bf16_f32 v68, v72, v73
	v_and_b32_e32 v150, v68, v188
	v_cvt_pk_bf16_f32 v68, v74, v75
	v_and_b32_e32 v151, v68, v188
	ds_read_b64_tr_b16 v[68:69], v189 offset:25600
	ds_read_b64_tr_b16 v[70:71], v189 offset:26112
	v_mfma_f32_32x32x16_bf16 v[100:115], v[172:175], v[120:123], v[100:115]
	v_add_f32_e32 v72, v78, v136
	v_add_f32_e32 v72, v79, v72
	v_add_f32_e32 v72, v80, v72
	v_add_f32_e32 v136, v81, v72
	v_cvt_pk_bf16_f32 v72, v76, v77
	v_and_b32_e32 v144, v72, v188
	v_cvt_pk_bf16_f32 v72, v78, v79
	v_and_b32_e32 v145, v72, v188
	ds_read_b64_tr_b16 v[72:73], v189 offset:29696
	ds_read_b64_tr_b16 v[74:75], v189 offset:30208
	v_mfma_f32_32x32x16_bf16 v[84:99], v[168:171], v[120:123], v[84:99]
	v_add_f32_e32 v76, v82, v136
	v_add_f32_e32 v76, v83, v76
	v_add_f32_e32 v76, v52, v76
	v_add_f32_e32 v136, v53, v76
	v_cvt_pk_bf16_f32 v76, v80, v81
	v_and_b32_e32 v146, v76, v188
	v_cvt_pk_bf16_f32 v76, v82, v83
	v_and_b32_e32 v147, v76, v188
	ds_read_b64_tr_b16 v[76:77], v189 offset:26624
	ds_read_b64_tr_b16 v[78:79], v189 offset:27136
	v_mfma_f32_32x32x16_bf16 v[100:115], v[164:167], v[124:127], v[100:115]
	v_add_f32_e32 v80, v54, v136
	v_add_f32_e32 v80, v55, v80
	v_cvt_pk_bf16_f32 v52, v52, v53
	v_add_f32_e32 v80, v56, v80
	v_and_b32_e32 v140, v52, v188
	v_cvt_pk_bf16_f32 v52, v54, v55
	v_add_f32_e32 v80, v57, v80
	v_and_b32_e32 v141, v52, v188
	ds_read_b64_tr_b16 v[52:53], v189 offset:30720
	ds_read_b64_tr_b16 v[54:55], v189 offset:31232
	v_mfma_f32_32x32x16_bf16 v[84:99], v[160:163], v[124:127], v[84:99]
	v_add_f32_e32 v80, v58, v80
	v_add_f32_e32 v80, v59, v80
	v_cvt_pk_bf16_f32 v56, v56, v57
	v_add_f32_e32 v80, v60, v80
	v_and_b32_e32 v142, v56, v188
	v_cvt_pk_bf16_f32 v56, v58, v59
	v_add_f32_e32 v80, v61, v80
	v_and_b32_e32 v143, v56, v188
	ds_read_b64_tr_b16 v[56:57], v189 offset:27648
	ds_read_b64_tr_b16 v[58:59], v189 offset:28160
	v_mfma_f32_32x32x16_bf16 v[100:115], v[156:159], v[128:131], v[100:115]
	v_add_f32_e32 v80, v62, v80
	v_add_f32_e32 v80, v63, v80
	v_cvt_pk_bf16_f32 v60, v60, v61
	v_add_f32_e32 v80, v64, v80
	v_and_b32_e32 v136, v60, v188
	v_cvt_pk_bf16_f32 v60, v62, v63
	v_add_f32_e32 v80, v65, v80
	v_and_b32_e32 v137, v60, v188
	ds_read_b64_tr_b16 v[60:61], v189 offset:31744
	ds_read_b64_tr_b16 v[62:63], v189 offset:32256
	v_mfma_f32_32x32x16_bf16 v[84:99], v[152:155], v[128:131], v[84:99]
	v_add_f32_e32 v80, v66, v80
	v_cvt_pk_bf16_f32 v64, v64, v65
	v_add_f32_e32 v80, v67, v80
	v_and_b32_e32 v138, v64, v188
	v_cvt_pk_bf16_f32 v64, v66, v67
	v_and_b32_e32 v139, v64, v188
	s_add_i32 s0, s25, 1
	s_cmp_ge_u32 s0, s48
	s_cselect_b64 s[10:11], -1, 0
	s_and_b64 vcc, exec, s[10:11]
	s_cbranch_vccnz .LBB0_817
	s_mov_b32 s22, 0xfffe0000
	s_mov_b32 s23, -1
	s_add_i32 s0, s54, s46
	v_lshl_add_u64 v[64:65], v[206:207], 0, s[22:23]
	s_mov_b32 m0, s0
	s_nop 0
	global_load_lds_dwordx4 v[64:65], off
.LBB0_817:
	s_add_i32 s0, s42, s47
	s_mov_b32 m0, s0
	s_nop 0
	global_load_lds_dwordx4 v[204:205], off
	s_add_i32 s24, s52, s25
	s_add_i32 s0, s24, -2
	s_cmp_lt_i32 s0, 0
	s_cbranch_scc1 .LBB0_819
	v_add_u32_e32 v65, 0xffffffa5, v222
	v_add_u32_e32 v64, 0xffffff85, v222
	v_cmp_le_i32_e32 vcc, v65, v216
	s_nop 1
	v_cndmask_b32_e32 v84, v232, v84, vcc
	v_cmp_lt_i32_e32 vcc, v64, v216
	s_nop 1
	v_cndmask_b32_e32 v101, v232, v101, vcc
	v_cmp_le_i32_e32 vcc, v64, v216
	v_add_u32_e32 v64, 0xffffffa6, v222
	s_nop 0
	v_cndmask_b32_e32 v100, v232, v100, vcc
	v_cmp_le_i32_e32 vcc, v64, v216
	v_add_u32_e32 v64, 0xffffff87, v222
	s_nop 0
	v_cndmask_b32_e32 v85, v232, v85, vcc
	v_cmp_le_i32_e32 vcc, v64, v216
	v_add_u32_e32 v64, 0xffffffa7, v222
	s_nop 0
	v_cndmask_b32_e32 v102, v232, v102, vcc
	v_cmp_le_i32_e32 vcc, v64, v216
	v_add_u32_e32 v64, 0xffffff88, v222
	s_nop 0
	v_cndmask_b32_e32 v86, v232, v86, vcc
	v_cmp_le_i32_e32 vcc, v64, v216
	v_add_u32_e32 v64, 0xffffffa8, v222
	s_nop 0
	v_cndmask_b32_e32 v103, v232, v103, vcc
	v_cmp_le_i32_e32 vcc, v64, v216
	v_add_u32_e32 v64, 0xffffff8d, v222
	s_nop 0
	v_cndmask_b32_e32 v87, v232, v87, vcc
	v_cmp_le_i32_e32 vcc, v64, v216
	v_add_u32_e32 v64, 0xffffffad, v222
	s_nop 0
	v_cndmask_b32_e32 v104, v232, v104, vcc
	v_cmp_le_i32_e32 vcc, v64, v216
	v_add_u32_e32 v64, 0xffffff8e, v222
	s_nop 0
	v_cndmask_b32_e32 v88, v232, v88, vcc
	v_cmp_le_i32_e32 vcc, v64, v216
	v_add_u32_e32 v64, 0xffffffae, v222
	s_nop 0
	v_cndmask_b32_e32 v105, v232, v105, vcc
	v_cmp_le_i32_e32 vcc, v64, v216
	v_add_u32_e32 v64, 0xffffff8f, v222
	s_nop 0
	v_cndmask_b32_e32 v89, v232, v89, vcc
	v_cmp_le_i32_e32 vcc, v64, v216
	v_add_u32_e32 v64, 0xffffffaf, v222
	s_nop 0
	v_cndmask_b32_e32 v106, v232, v106, vcc
	v_cmp_le_i32_e32 vcc, v64, v216
	v_add_u32_e32 v64, 0xffffff90, v222
	s_nop 0
	v_cndmask_b32_e32 v90, v232, v90, vcc
	v_cmp_le_i32_e32 vcc, v64, v216
	v_add_u32_e32 v64, 0xffffffb0, v222
	s_nop 0
	v_cndmask_b32_e32 v107, v232, v107, vcc
	v_cmp_le_i32_e32 vcc, v64, v216
	v_add_u32_e32 v64, 0xffffff95, v222
	s_nop 0
	v_cndmask_b32_e32 v91, v232, v91, vcc
	v_cmp_le_i32_e32 vcc, v64, v216
	v_add_u32_e32 v64, 0xffffffb5, v222
	s_nop 0
	v_cndmask_b32_e32 v108, v232, v108, vcc
	v_cmp_le_i32_e32 vcc, v64, v216
	v_add_u32_e32 v64, 0xffffff96, v222
	s_nop 0
	v_cndmask_b32_e32 v92, v232, v92, vcc
	v_cmp_le_i32_e32 vcc, v64, v216
	v_add_u32_e32 v64, 0xffffffb6, v222
	s_nop 0
	v_cndmask_b32_e32 v109, v232, v109, vcc
	v_cmp_le_i32_e32 vcc, v64, v216
	v_add_u32_e32 v64, 0xffffff97, v222
	s_nop 0
	v_cndmask_b32_e32 v93, v232, v93, vcc
	v_cmp_le_i32_e32 vcc, v64, v216
	v_add_u32_e32 v64, 0xffffffb7, v222
	s_nop 0
	v_cndmask_b32_e32 v110, v232, v110, vcc
	v_cmp_le_i32_e32 vcc, v64, v216
	v_add_u32_e32 v64, 0xffffff98, v222
	s_nop 0
	v_cndmask_b32_e32 v94, v232, v94, vcc
	v_cmp_le_i32_e32 vcc, v64, v216
	v_add_u32_e32 v64, 0xffffffb8, v222
	s_nop 0
	v_cndmask_b32_e32 v111, v232, v111, vcc
	v_cmp_le_i32_e32 vcc, v64, v216
	v_add_u32_e32 v64, 0xffffff9d, v222
	s_nop 0
	v_cndmask_b32_e32 v95, v232, v95, vcc
	v_cmp_le_i32_e32 vcc, v64, v216
	v_add_u32_e32 v64, 0xffffffbd, v222
	s_nop 0
	v_cndmask_b32_e32 v112, v232, v112, vcc
	v_cmp_le_i32_e32 vcc, v64, v216
	v_add_u32_e32 v64, 0xffffff9e, v222
	s_nop 0
	v_cndmask_b32_e32 v96, v232, v96, vcc
	v_cmp_le_i32_e32 vcc, v64, v216
	v_add_u32_e32 v64, 0xffffffbe, v222
	s_nop 0
	v_cndmask_b32_e32 v113, v232, v113, vcc
	v_cmp_le_i32_e32 vcc, v64, v216
	v_add_u32_e32 v64, 0xffffff9f, v222
	s_nop 0
	v_cndmask_b32_e32 v97, v232, v97, vcc
	v_cmp_le_i32_e32 vcc, v64, v216
	v_add_u32_e32 v64, 0xffffffbf, v222
	s_nop 0
	v_cndmask_b32_e32 v114, v232, v114, vcc
	v_cmp_le_i32_e32 vcc, v64, v216
	v_add_u32_e32 v64, 0xffffffa0, v222
	s_nop 0
	v_cndmask_b32_e32 v98, v232, v98, vcc
	v_cmp_le_i32_e32 vcc, v64, v216
	v_subrev_u32_e32 v64, 64, v222
	s_nop 0
	v_cndmask_b32_e32 v115, v232, v115, vcc
	v_cmp_le_i32_e32 vcc, v64, v216
	s_nop 1
	v_cndmask_b32_e32 v99, v232, v99, vcc

.LBB0_824:
	v_alignbit_b32 v132, v133, v132, 1
	v_bfe_i32 v203, v132, 0, 1
	v_add_u32_e32 v196, s54, v219
	ds_read_b64_tr_b16 v[188:189], v196 offset:24576
	ds_read_b64_tr_b16 v[190:191], v196 offset:25088
	v_mfma_f32_32x32x16_bf16 v[68:83], v[180:183], v[116:119], v[36:51]
	v_add_f32_e32 v52, v100, v101
	v_add_f32_e32 v52, v102, v52
	v_add_f32_e32 v52, v103, v52
	v_cvt_pk_bf16_f32 v53, v100, v101
	v_add_f32_e32 v52, v104, v52
	v_and_b32_e32 v148, v53, v203
	v_cvt_pk_bf16_f32 v53, v102, v103
	v_add_f32_e32 v52, v105, v52
	v_and_b32_e32 v149, v53, v203
	ds_read_b64_tr_b16 v[192:193], v196 offset:28672
	ds_read_b64_tr_b16 v[194:195], v196 offset:29184
	v_add_f32_e32 v52, v106, v52
	v_add_f32_e32 v52, v107, v52
	v_add_f32_e32 v52, v108, v52
	v_add_f32_e32 v100, v109, v52
	v_mfma_f32_32x32x16_bf16 v[52:67], v[176:179], v[116:119], v[36:51]
	v_cvt_pk_bf16_f32 v101, v104, v105
	v_and_b32_e32 v150, v101, v203
	v_cvt_pk_bf16_f32 v101, v106, v107
	v_and_b32_e32 v151, v101, v203
	ds_read_b64_tr_b16 v[184:185], v196 offset:25600
	ds_read_b64_tr_b16 v[186:187], v196 offset:26112
	v_mfma_f32_32x32x16_bf16 v[68:83], v[172:175], v[120:123], v[68:83]
	v_add_f32_e32 v100, v110, v100
	v_add_f32_e32 v100, v111, v100
	v_cvt_pk_bf16_f32 v101, v108, v109
	v_add_f32_e32 v100, v112, v100
	v_and_b32_e32 v144, v101, v203
	v_cvt_pk_bf16_f32 v101, v110, v111
	v_add_f32_e32 v100, v113, v100
	v_and_b32_e32 v145, v101, v203
	ds_read_b64_tr_b16 v[104:105], v196 offset:29696
	ds_read_b64_tr_b16 v[106:107], v196 offset:30208
	v_mfma_f32_32x32x16_bf16 v[52:67], v[168:171], v[120:123], v[52:67]
	v_add_f32_e32 v100, v114, v100
	v_add_f32_e32 v100, v115, v100
	v_add_f32_e32 v100, v84, v100
	v_add_f32_e32 v108, v85, v100
	v_cvt_pk_bf16_f32 v100, v112, v113
	v_and_b32_e32 v146, v100, v203
	v_cvt_pk_bf16_f32 v100, v114, v115
	v_and_b32_e32 v147, v100, v203
	ds_read_b64_tr_b16 v[100:101], v196 offset:26624
	ds_read_b64_tr_b16 v[102:103], v196 offset:27136
	v_mfma_f32_32x32x16_bf16 v[68:83], v[164:167], v[124:127], v[68:83]
	v_add_f32_e32 v108, v86, v108
	v_add_f32_e32 v108, v87, v108
	v_cvt_pk_bf16_f32 v84, v84, v85
	v_add_f32_e32 v108, v88, v108
	v_and_b32_e32 v140, v84, v203
	v_cvt_pk_bf16_f32 v84, v86, v87
	v_add_f32_e32 v108, v89, v108
	v_and_b32_e32 v141, v84, v203
	ds_read_b64_tr_b16 v[84:85], v196 offset:30720
	ds_read_b64_tr_b16 v[86:87], v196 offset:31232
	v_mfma_f32_32x32x16_bf16 v[52:67], v[160:163], v[124:127], v[52:67]
	v_add_f32_e32 v108, v90, v108
	v_add_f32_e32 v108, v91, v108
	v_cvt_pk_bf16_f32 v88, v88, v89
	v_add_f32_e32 v108, v92, v108
	v_and_b32_e32 v142, v88, v203
	v_cvt_pk_bf16_f32 v88, v90, v91
	v_add_f32_e32 v108, v93, v108
	v_and_b32_e32 v143, v88, v203
	ds_read_b64_tr_b16 v[88:89], v196 offset:27648
	ds_read_b64_tr_b16 v[90:91], v196 offset:28160
	v_mfma_f32_32x32x16_bf16 v[68:83], v[156:159], v[128:131], v[68:83]
	v_add_f32_e32 v108, v94, v108
	v_add_f32_e32 v108, v95, v108
	v_cvt_pk_bf16_f32 v92, v92, v93
	v_add_f32_e32 v108, v96, v108
	v_and_b32_e32 v136, v92, v203
	v_cvt_pk_bf16_f32 v92, v94, v95
	v_add_f32_e32 v108, v97, v108
	v_and_b32_e32 v137, v92, v203
	ds_read_b64_tr_b16 v[92:93], v196 offset:31744
	ds_read_b64_tr_b16 v[94:95], v196 offset:32256
	v_mfma_f32_32x32x16_bf16 v[52:67], v[152:155], v[128:131], v[52:67]
	v_add_f32_e32 v108, v98, v108
	v_cvt_pk_bf16_f32 v96, v96, v97
	v_add_f32_e32 v108, v99, v108
	v_and_b32_e32 v138, v96, v203
	v_cvt_pk_bf16_f32 v96, v98, v99
	v_and_b32_e32 v139, v96, v203
	s_add_i32 s55, s25, 2
	s_cmp_ge_u32 s55, s48
	s_cselect_b64 s[22:23], -1, 0
	s_and_b64 vcc, exec, s[22:23]
	s_cbranch_vccnz .LBB0_826
	s_add_i32 s0, s42, s46
	s_mov_b32 m0, s0
	s_nop 0
	global_load_lds_dwordx4 v[206:207], off
.LBB0_826:
	s_add_i32 s0, s42, 0x2000
	s_cmpk_lg_i32 s42, 0x4000
	s_cselect_b32 s54, s0, 0
	s_cmp_lt_u32 s25, s48
	s_cselect_b64 s[26:27], -1, 0
	s_cmp_ge_u32 s25, s48
	s_cbranch_scc1 .LBB0_828
	s_mov_b64 s[56:57], 0x20000
	s_add_i32 s0, s54, s47
	v_lshl_add_u64 v[96:97], v[204:205], 0, s[56:57]
	s_mov_b32 m0, s0
	s_nop 0
	global_load_lds_dwordx4 v[96:97], off

.LBB0_864:
	s_waitcnt vmcnt(0)
	v_bfe_i32 v133, v132, 0, 1
	v_add_u32_e32 v134, s42, v219
	ds_read_b64_tr_b16 v[100:101], v134 offset:24576
	ds_read_b64_tr_b16 v[102:103], v134 offset:25088
	v_add_f32_e32 v84, v68, v69
	v_add_f32_e32 v84, v70, v84
	v_add_f32_e32 v84, v71, v84
	v_add_f32_e32 v84, v72, v84
	v_add_f32_e32 v108, v73, v84
	v_mfma_f32_32x32x16_bf16 v[84:99], v[180:183], v[116:119], v[36:51]
	v_cvt_pk_bf16_f32 v68, v68, v69
	v_and_b32_e32 v148, v133, v68
	v_cvt_pk_bf16_f32 v68, v70, v71
	v_and_b32_e32 v149, v133, v68
	ds_read_b64_tr_b16 v[104:105], v134 offset:28672
	ds_read_b64_tr_b16 v[106:107], v134 offset:29184
	v_mfma_f32_32x32x16_bf16 v[36:51], v[176:179], v[116:119], v[36:51]
	v_add_f32_e32 v68, v74, v108
	v_add_f32_e32 v68, v75, v68
	v_cvt_pk_bf16_f32 v69, v72, v73
	v_add_f32_e32 v68, v76, v68
	v_and_b32_e32 v150, v133, v69
	v_cvt_pk_bf16_f32 v69, v74, v75
	v_add_f32_e32 v68, v77, v68
	v_and_b32_e32 v151, v133, v69
	ds_read_b64_tr_b16 v[108:109], v134 offset:25600
	ds_read_b64_tr_b16 v[110:111], v134 offset:26112
	v_mfma_f32_32x32x16_bf16 v[84:99], v[172:175], v[120:123], v[84:99]
	v_add_f32_e32 v68, v78, v68
	v_add_f32_e32 v68, v79, v68
	v_cvt_pk_bf16_f32 v69, v76, v77
	v_add_f32_e32 v68, v80, v68
	v_and_b32_e32 v144, v133, v69
	v_cvt_pk_bf16_f32 v69, v78, v79
	v_add_f32_e32 v68, v81, v68
	v_and_b32_e32 v145, v133, v69
	ds_read_b64_tr_b16 v[112:113], v134 offset:29696
	ds_read_b64_tr_b16 v[114:115], v134 offset:30208
	v_mfma_f32_32x32x16_bf16 v[36:51], v[168:171], v[120:123], v[36:51]
	v_add_f32_e32 v68, v82, v68
	v_add_f32_e32 v68, v83, v68
	v_cvt_pk_bf16_f32 v69, v80, v81
	v_add_f32_e32 v68, v52, v68
	v_and_b32_e32 v146, v133, v69
	v_cvt_pk_bf16_f32 v69, v82, v83
	v_add_f32_e32 v68, v53, v68
	v_and_b32_e32 v147, v133, v69
	ds_read_b64_tr_b16 v[168:169], v134 offset:26624
	ds_read_b64_tr_b16 v[170:171], v134 offset:27136
	v_mfma_f32_32x32x16_bf16 v[84:99], v[164:167], v[124:127], v[84:99]
	v_add_f32_e32 v68, v54, v68
	v_add_f32_e32 v68, v55, v68
	v_cvt_pk_bf16_f32 v52, v52, v53
	v_add_f32_e32 v68, v56, v68
	v_and_b32_e32 v140, v133, v52
	v_cvt_pk_bf16_f32 v52, v54, v55
	v_add_f32_e32 v68, v57, v68
	v_and_b32_e32 v141, v133, v52
	ds_read_b64_tr_b16 v[164:165], v134 offset:30720
	ds_read_b64_tr_b16 v[166:167], v134 offset:31232
	v_mfma_f32_32x32x16_bf16 v[36:51], v[160:163], v[124:127], v[36:51]
	v_add_f32_e32 v52, v58, v68
	v_add_f32_e32 v52, v59, v52
	v_cvt_pk_bf16_f32 v53, v56, v57
	v_add_f32_e32 v52, v60, v52
	v_and_b32_e32 v142, v133, v53
	v_cvt_pk_bf16_f32 v53, v58, v59
	v_add_f32_e32 v52, v61, v52
	v_and_b32_e32 v143, v133, v53
	ds_read_b64_tr_b16 v[160:161], v134 offset:27648
	ds_read_b64_tr_b16 v[162:163], v134 offset:28160
	v_mfma_f32_32x32x16_bf16 v[84:99], v[156:159], v[128:131], v[84:99]
	v_add_f32_e32 v52, v62, v52
	v_add_f32_e32 v52, v63, v52
	v_cvt_pk_bf16_f32 v53, v60, v61
	v_add_f32_e32 v52, v64, v52
	v_and_b32_e32 v136, v133, v53
	v_cvt_pk_bf16_f32 v53, v62, v63
	v_add_f32_e32 v52, v65, v52
	v_and_b32_e32 v137, v133, v53
	ds_read_b64_tr_b16 v[156:157], v134 offset:31744
	ds_read_b64_tr_b16 v[158:159], v134 offset:32256
	v_mfma_f32_32x32x16_bf16 v[36:51], v[152:155], v[128:131], v[36:51]
	v_add_f32_e32 v52, v66, v52
	v_cvt_pk_bf16_f32 v53, v64, v65
	v_add_f32_e32 v52, v67, v52
	v_and_b32_e32 v138, v133, v53
	v_cvt_pk_bf16_f32 v53, v66, v67
	v_and_b32_e32 v139, v133, v53
	v_or_b32_e32 v53, 0xe0, v215
	v_and_b32_e32 v68, v52, v133
	v_or_b32_e32 v52, 0xc0, v215
	v_cmp_le_i32_e32 vcc, v53, v216
	v_or_b32_e32 v54, 0xe1, v215
	v_or_b32_e32 v55, 0xe2, v215
	v_cndmask_b32_e32 v36, v232, v36, vcc
	v_cmp_lt_i32_e32 vcc, v52, v216
	v_or_b32_e32 v56, 0xe3, v215
	v_or_b32_e32 v57, 0xe8, v215
	v_cndmask_b32_e32 v53, v232, v85, vcc
	v_cmp_le_i32_e32 vcc, v52, v216
	v_or_b32_e32 v58, 0xe9, v215
	v_or_b32_e32 v59, 0xea, v215
	v_cndmask_b32_e32 v52, v232, v84, vcc
	v_cmp_le_i32_e32 vcc, v54, v216
	v_or_b32_e32 v54, 0xc2, v215
	v_or_b32_e32 v60, 0xeb, v215
	v_cndmask_b32_e32 v37, v232, v37, vcc
	v_cmp_le_i32_e32 vcc, v54, v216
	v_or_b32_e32 v61, 0xf0, v215
	v_or_b32_e32 v62, 0xf1, v215
	v_cndmask_b32_e32 v54, v232, v86, vcc
	v_cmp_le_i32_e32 vcc, v55, v216
	v_or_b32_e32 v55, 0xc3, v215
	v_or_b32_e32 v63, 0xf2, v215
	v_cndmask_b32_e32 v38, v232, v38, vcc
	v_cmp_le_i32_e32 vcc, v55, v216
	v_or_b32_e32 v64, 0xf3, v215
	v_or_b32_e32 v65, 0xf8, v215
	v_cndmask_b32_e32 v55, v232, v87, vcc
	v_cmp_le_i32_e32 vcc, v56, v216
	v_or_b32_e32 v56, 0xc8, v215
	v_or_b32_e32 v66, 0xf9, v215
	v_cndmask_b32_e32 v39, v232, v39, vcc
	v_cmp_le_i32_e32 vcc, v56, v216
	v_or_b32_e32 v67, 0xfa, v215
	v_or_b32_e32 v69, 0xfb, v215
	v_cndmask_b32_e32 v56, v232, v88, vcc
	v_cmp_le_i32_e32 vcc, v57, v216
	v_or_b32_e32 v57, 0xc9, v215
	v_max_f32_e32 v70, v52, v52
	v_cndmask_b32_e32 v40, v232, v40, vcc
	v_cmp_le_i32_e32 vcc, v57, v216
	v_add_f32_e32 v86, v220, v68
	s_nop 0
	v_cndmask_b32_e32 v57, v232, v89, vcc
	v_cmp_le_i32_e32 vcc, v58, v216
	v_or_b32_e32 v58, 0xca, v215
	s_nop 0
	v_cndmask_b32_e32 v41, v232, v41, vcc
	v_cmp_le_i32_e32 vcc, v58, v216
	s_nop 1
	v_cndmask_b32_e32 v58, v232, v90, vcc
	v_cmp_le_i32_e32 vcc, v59, v216
	v_or_b32_e32 v59, 0xcb, v215
	s_nop 0
	v_cndmask_b32_e32 v42, v232, v42, vcc
	v_cmp_le_i32_e32 vcc, v59, v216
	s_nop 1
	v_cndmask_b32_e32 v59, v232, v91, vcc
	v_cmp_le_i32_e32 vcc, v60, v216
	v_or_b32_e32 v60, 0xd0, v215
	s_nop 0
	v_cndmask_b32_e32 v43, v232, v43, vcc
	v_cmp_le_i32_e32 vcc, v60, v216
	s_nop 1
	v_cndmask_b32_e32 v60, v232, v92, vcc
	v_cmp_le_i32_e32 vcc, v61, v216
	v_or_b32_e32 v61, 0xd1, v215
	s_nop 0
	v_cndmask_b32_e32 v44, v232, v44, vcc
	v_cmp_le_i32_e32 vcc, v61, v216
	s_nop 1
	v_cndmask_b32_e32 v61, v232, v93, vcc
	v_cmp_le_i32_e32 vcc, v62, v216
	v_or_b32_e32 v62, 0xd2, v215
	s_nop 0
	v_cndmask_b32_e32 v45, v232, v45, vcc
	v_cmp_le_i32_e32 vcc, v62, v216
	s_nop 1
	v_cndmask_b32_e32 v62, v232, v94, vcc
	v_cmp_le_i32_e32 vcc, v63, v216
	v_or_b32_e32 v63, 0xd3, v215
	s_nop 0
	v_cndmask_b32_e32 v46, v232, v46, vcc
	v_cmp_le_i32_e32 vcc, v63, v216
	s_nop 1
	v_cndmask_b32_e32 v63, v232, v95, vcc
	v_cmp_le_i32_e32 vcc, v64, v216
	v_or_b32_e32 v64, 0xd8, v215
	s_nop 0
	v_cndmask_b32_e32 v47, v232, v47, vcc
	v_cmp_le_i32_e32 vcc, v64, v216
	s_nop 1
	v_cndmask_b32_e32 v64, v232, v96, vcc
	v_cmp_le_i32_e32 vcc, v65, v216
	v_or_b32_e32 v65, 0xd9, v215
	s_nop 0
	v_cndmask_b32_e32 v48, v232, v48, vcc
	v_cmp_le_i32_e32 vcc, v65, v216
	s_nop 1
	v_cndmask_b32_e32 v65, v232, v97, vcc
	v_cmp_le_i32_e32 vcc, v66, v216
	v_or_b32_e32 v66, 0xda, v215
	s_nop 0
	v_cndmask_b32_e32 v49, v232, v49, vcc
	v_cmp_le_i32_e32 vcc, v66, v216
	s_nop 1
	v_cndmask_b32_e32 v66, v232, v98, vcc
	v_cmp_le_i32_e32 vcc, v67, v216
	v_or_b32_e32 v67, 0xdb, v215
	s_nop 0
	v_cndmask_b32_e32 v50, v232, v50, vcc
	v_cmp_le_i32_e32 vcc, v67, v216
	s_nop 1
	v_cndmask_b32_e32 v67, v232, v99, vcc
	v_cmp_le_i32_e32 vcc, v69, v216
	v_max_f32_e32 v69, v53, v53
	v_max_f32_e32 v69, v70, v69
	v_max3_f32 v70, v54, v55, v37
	v_max3_f32 v69, v69, v36, v38
	v_max3_f32 v69, v69, v39, v56
	v_max3_f32 v70, v70, v58, v59
	v_max3_f32 v69, v69, v57, v40
	v_max3_f32 v70, v70, v42, v43
	v_max3_f32 v69, v69, v41, v60
	v_max3_f32 v70, v70, v62, v63
	v_max3_f32 v69, v69, v61, v44
	v_max3_f32 v70, v70, v46, v47
	v_cndmask_b32_e32 v51, v232, v51, vcc
	v_max3_f32 v69, v69, v45, v64
	v_max3_f32 v70, v70, v66, v67
	v_max3_f32 v69, v69, v65, v48
	v_max3_f32 v70, v70, v50, v51
	v_max3_f32 v68, v69, v49, v70
	v_mov_b32_e32 v69, v68
	s_nop 1
	v_permlane32_swap_b32_e32 v68, v69
	v_max_f32_e32 v69, v69, v69
	v_max_f32_e32 v68, v68, v68
	v_max_f32_e32 v68, v68, v69
	v_cmp_lt_f32_e32 vcc, s33, v68
	s_cmp_lg_u64 vcc, 0
	s_cselect_b64 s[0:1], -1, 0
	s_cbranch_vccnz .LBB0_980

.LBB0_869:
	s_or_b64 exec, exec, s[0:1]
	s_add_u32 s42, s50, 0x28400000
	s_addc_u32 s43, s49, 0
	s_lshl_b64 s[0:1], s[18:19], 1
	s_add_u32 s0, s42, s0
	s_addc_u32 s1, s43, s1
	s_lshl_b64 s[8:9], s[8:9], 1
	s_add_u32 s0, s0, s8
	v_and_b32_e32 v88, 56, v212
	s_addc_u32 s1, s1, s9
	v_lshlrev_b32_e32 v68, 1, v88
	v_mov_b32_e32 v69, v3
	v_lshl_add_u64 v[84:85], s[0:1], 0, v[68:69]
	v_lshlrev_b32_e32 v68, 8, v1
	v_and_b32_e32 v68, 0x3800, v68
	v_lshl_add_u64 v[68:69], v[84:85], 0, v[68:69]
	s_movk_i32 s0, 0x4000
	v_add_co_u32_e64 v70, s[0:1], s0, v68
	v_add_f32_e32 v91, v52, v53
	s_nop 0
	v_addc_co_u32_e64 v71, s[0:1], 0, v69, s[0:1]
	s_mov_b32 s0, 0x8000
	global_load_dwordx4 v[80:83], v[68:69], off
	global_load_dwordx4 v[76:79], v[70:71], off
	v_add_co_u32_e64 v70, s[0:1], s0, v68
	v_add_f32_e32 v91, v54, v91
	s_nop 0
	v_addc_co_u32_e64 v71, s[0:1], 0, v69, s[0:1]
	s_mov_b32 s0, 0xc000
	s_nop 0
	v_add_co_u32_e64 v68, s[0:1], s0, v68
	v_add_f32_e32 v91, v55, v91
	s_nop 0
	v_addc_co_u32_e64 v69, s[0:1], 0, v69, s[0:1]
	global_load_dwordx4 v[72:75], v[70:71], off
	s_nop 0
	global_load_dwordx4 v[68:71], v[68:69], off
	v_add_f32_e32 v91, v56, v91
	v_add_f32_e32 v91, v57, v91
	v_add_f32_e32 v91, v58, v91
	s_add_u32 s55, s50, 0x25200000
	v_add_f32_e32 v91, v59, v91
	s_addc_u32 s56, s49, 0
	v_add_f32_e32 v91, v60, v91
	s_cmp_gt_u32 s51, 1
	v_add_f32_e32 v91, v61, v91
	s_cselect_b64 s[22:23], -1, 0
	s_lshl_b32 s52, s51, 2
	v_add_f32_e32 v91, v62, v91
	s_add_i32 s18, s52, -8
	s_mov_b32 s19, s65
	v_add_f32_e32 v91, v63, v91
	s_lshl_b64 s[4:5], s[18:19], 15
	v_add_f32_e32 v91, v64, v91
	s_and_b64 s[20:21], s[22:23], exec
	v_add_f32_e32 v91, v65, v91
	s_cselect_b32 s5, s5, 0
	s_cselect_b32 s4, s4, 0
	s_lshl_b64 s[26:27], s[16:17], 22
	v_add_f32_e32 v91, v66, v91
	s_add_u32 s4, s4, s26
	v_add_f32_e32 v91, v67, v91
	s_addc_u32 s5, s5, s27
	v_add_f32_e32 v91, v36, v91
	s_lshl_b64 s[16:17], s[4:5], 1
	v_add_f32_e32 v91, v37, v91
	s_add_u32 s19, s55, s16
	v_add_f32_e32 v91, v38, v91
	s_addc_u32 s20, s56, s17
	s_lshl_b32 s4, s39, 4
	v_add_f32_e32 v91, v39, v91
	s_andn2_b32 s4, s4, 63
	v_add_f32_e32 v91, v40, v91
	s_ashr_i32 s5, s4, 31
	v_add_f32_e32 v91, v41, v91
	s_lshl_b64 s[4:5], s[4:5], 1
	v_add_f32_e32 v91, v42, v91
	s_add_u32 s0, s19, s4
	v_add_f32_e32 v91, v43, v91
	s_addc_u32 s1, s20, s5
	v_add_f32_e32 v91, v44, v91
	s_add_u32 s50, s50, 0x25200200
	v_add_f32_e32 v91, v45, v91
	s_addc_u32 s49, s49, 0
	v_add_f32_e32 v91, v46, v91
	s_add_u32 s16, s50, s16
	v_add_f32_e32 v91, v47, v91
	s_addc_u32 s17, s49, s17
	v_add_f32_e32 v91, v48, v91
	s_add_u32 s16, s16, s4
	v_add_f32_e32 v91, v49, v91
	s_addc_u32 s17, s17, s5
	v_add_f32_e32 v91, v50, v91
	s_cmp_lg_u32 0, -1
	v_add_f32_e32 v91, v51, v91
	v_bfe_i32 v92, v132, 1, 1
	s_cselect_b32 s19, 0, 0
	v_and_b32_e32 v91, v92, v91
	s_add_i32 s20, s19, 0x6000
	v_add_f32_e32 v86, v86, v91
	v_cvt_pk_bf16_f32 v52, v52, v53
	v_cvt_pk_bf16_f32 v53, v54, v55
	v_cvt_pk_bf16_f32 v54, v56, v57
	v_cvt_pk_bf16_f32 v55, v58, v59
	v_cvt_pk_bf16_f32 v56, v60, v61
	v_cvt_pk_bf16_f32 v57, v62, v63
	v_cvt_pk_bf16_f32 v58, v64, v65
	v_cvt_pk_bf16_f32 v59, v66, v67
	v_cvt_pk_bf16_f32 v36, v36, v37
	v_cvt_pk_bf16_f32 v37, v38, v39
	v_cvt_pk_bf16_f32 v38, v40, v41
	v_cvt_pk_bf16_f32 v39, v42, v43
	v_cvt_pk_bf16_f32 v40, v44, v45
	v_cvt_pk_bf16_f32 v41, v46, v47
	v_cvt_pk_bf16_f32 v42, v48, v49
	v_cvt_pk_bf16_f32 v43, v50, v51
	v_add3_u32 v90, v214, s20, v211
	v_and_b32_e32 v52, v92, v52
	v_and_b32_e32 v53, v92, v53
	v_and_b32_e32 v54, v92, v54
	v_and_b32_e32 v55, v92, v55
	v_and_b32_e32 v56, v92, v56
	v_and_b32_e32 v57, v92, v57
	v_and_b32_e32 v58, v92, v58
	v_and_b32_e32 v59, v92, v59
	v_and_b32_e32 v36, v92, v36
	v_and_b32_e32 v37, v92, v37
	v_and_b32_e32 v38, v92, v38
	v_and_b32_e32 v39, v92, v39
	v_and_b32_e32 v40, v92, v40
	v_and_b32_e32 v41, v92, v41
	v_and_b32_e32 v42, v92, v42
	v_and_b32_e32 v43, v92, v43
	v_add3_u32 v90, v90, v213, s54
	ds_read_b64_tr_b16 v[44:45],v90 offset:0
	ds_read_b64_tr_b16 v[46:47],v90 offset:512
	ds_read_b64_tr_b16 v[48:49],v90 offset:1024
	ds_read_b64_tr_b16 v[50:51],v90 offset:1536
	ds_read_b64_tr_b16 v[60:61],v90 offset:2048
	ds_read_b64_tr_b16 v[62:63],v90 offset:2560
	ds_read_b64_tr_b16 v[64:65],v90 offset:3072
	ds_read_b64_tr_b16 v[66:67],v90 offset:3584
	s_waitcnt lgkmcnt(0)
	s_nop 0
	v_mfma_f32_32x32x16_bf16 v[20:35], v[52:55], v[44:47], v[20:35]
	ds_read_b64_tr_b16 v[44:45],v90 offset:4096
	ds_read_b64_tr_b16 v[46:47],v90 offset:4608
	v_mfma_f32_32x32x16_bf16 v[20:35], v[56:59], v[48:51], v[20:35]
	ds_read_b64_tr_b16 v[48:49],v90 offset:5120
	ds_read_b64_tr_b16 v[50:51],v90 offset:5632
	v_mfma_f32_32x32x16_bf16 v[20:35], v[36:39], v[60:63], v[20:35]
	ds_read_b64_tr_b16 v[60:61],v90 offset:6144
	ds_read_b64_tr_b16 v[62:63],v90 offset:6656
	v_mfma_f32_32x32x16_bf16 v[20:35], v[40:43], v[64:67], v[20:35]
	ds_read_b64_tr_b16 v[64:65],v90 offset:7168
	ds_read_b64_tr_b16 v[66:67],v90 offset:7680
	s_waitcnt lgkmcnt(0)
	v_mfma_f32_32x32x16_bf16 v[4:19], v[52:55], v[44:47], v[4:19]
	v_lshlrev_b32_e32 v44, 10, v1
	v_mov_b32_e32 v45, v3
	v_lshlrev_b32_e32 v46, 10, v210
	v_mov_b32_e32 v47, v3
	s_waitcnt lgkmcnt(0)
	s_barrier
	v_lshl_add_u64 v[44:45], s[0:1], 0, v[44:45]
	v_lshl_add_u64 v[46:47], s[16:17], 0, v[46:47]
	v_mfma_f32_32x32x16_bf16 v[4:19], v[56:59], v[48:51], v[4:19]
	v_lshl_add_u64 v[44:45], s[12:13], 1, v[44:45]
	v_lshl_add_u64 v[46:47], s[14:15], 1, v[46:47]
	s_mov_b32 m0, s46
	s_nop 0
	global_load_lds_dwordx4 v[44:45], off
	v_lshl_add_u64 v[46:47], v[46:47], 0, v[2:3]
	s_mov_b32 m0, s47
	s_nop 0
	global_load_lds_dwordx4 v[46:47], off
	s_mov_b64 s[0:1], 0x10000
	v_mov_b32_e32 v2, v86
	v_mfma_f32_32x32x16_bf16 v[4:19], v[36:39], v[60:63], v[4:19]
	v_lshl_add_u64 v[36:37], v[44:45], 0, s[0:1]
	s_add_i32 s0, s19, s45
	s_addk_i32 s0, 0x2000
	s_mov_b32 m0, s0
	s_nop 0
	global_load_lds_dwordx4 v[36:37], off
	v_permlane32_swap_b32_e32 v86, v2
	v_mfma_f32_32x32x16_bf16 v[4:19], v[40:43], v[64:67], v[4:19]
	s_and_saveexec_b64 s[0:1], vcc
	s_cbranch_execz .LBB0_871
	v_add_f32_e32 v2, v86, v2
	v_rcp_f32_e32 v2, v2
	v_lshl_add_u32 v36, v208, 2, s53
	s_waitcnt vmcnt(4)
	v_mul_f32_e32 v2, v89, v2
	ds_write_b32 v36, v2 offset:49280

.LBB0_879:
	v_mov_b32_e32 v52, v0
	s_mov_b32 s25, s65
	v_readfirstlane_b32 s28, v52
	s_ashr_i32 s45, s28, 6
	s_lshl_b32 s47, s45, 5
	s_and_b64 s[0:1], s[22:23], exec
	s_cselect_b32 s24, s18, 0
	s_lshl_b64 s[0:1], s[24:25], 15
	s_add_u32 s0, s0, s26
	s_addc_u32 s1, s1, s27
	s_lshl_b32 s18, s45, 3
	s_ashr_i32 s19, s18, 31
	s_lshl_b32 s46, s45, 10
	s_lshl_b64 s[26:27], s[0:1], 1
	s_add_u32 s0, s55, s26
	s_addc_u32 s1, s56, s27
	v_and_b32_e32 v1, 63, v52
	s_add_u32 s0, s0, s4
	v_lshlrev_b32_e32 v2, 10, v1
	s_addc_u32 s1, s1, s5
	v_and_b32_e32 v218, 31, v52
	v_bfe_u32 v219, v52, 5, 1
	v_mov_b32_e32 v4, v3
	v_lshl_add_u64 v[20:21], s[0:1], 0, v[2:3]
	s_sub_i32 s51, s48, s24
	v_lshlrev_b32_e32 v22, 10, v219
	v_lshlrev_b32_e32 v23, 4, v218
	v_lshl_add_u64 v[206:207], s[18:19], 1, v[20:21]
	v_mov_b32_e32 v18, v4
	v_mov_b32_e32 v19, v4
	s_mov_b64 s[0:1], 0x20000
	s_cmp_lg_u32 0, -1
	v_mov_b32_e32 v5, v4
	v_mov_b32_e32 v6, v4
	v_mov_b32_e32 v7, v4
	v_mov_b32_e32 v8, v4
	v_mov_b32_e32 v9, v4
	v_mov_b32_e32 v10, v4
	v_mov_b32_e32 v11, v4
	v_mov_b32_e32 v12, v4
	v_mov_b32_e32 v13, v4
	v_mov_b32_e32 v14, v4
	v_mov_b32_e32 v15, v4
	v_mov_b32_e32 v16, v4
	v_mov_b32_e32 v17, v4
	v_add3_u32 v246, 0, v22, v23
	v_mov_b64_e32 v[34:35], v[18:19]
	v_lshl_add_u64 v[36:37], v[206:207], 0, s[0:1]
	s_cselect_b32 s0, 0, 0
	v_mov_b64_e32 v[32:33], v[16:17]
	v_mov_b64_e32 v[30:31], v[14:15]
	v_mov_b64_e32 v[28:29], v[12:13]
	v_mov_b64_e32 v[26:27], v[10:11]
	v_mov_b64_e32 v[24:25], v[8:9]
	v_mov_b64_e32 v[22:23], v[6:7]
	v_mov_b64_e32 v[20:21], v[4:5]
	s_add_i32 s0, s0, s46
	s_addk_i32 s0, 0x4000
	s_mov_b32 m0, s0
	s_nop 0
	global_load_lds_dwordx4 v[36:37], off
	s_waitcnt vmcnt(3) lgkmcnt(0)
	s_barrier
	ds_read_b128 v[54:57], v246
	s_waitcnt lgkmcnt(0)
	v_mfma_f32_32x32x16_bf16 v[36:51], v[54:57], v[116:119], v[20:35]
	ds_read_b128 v[54:57], v246 offset:512
	v_or_b32_e32 v204, s47, v218
	s_cmp_gt_i32 s51, 4
	v_lshlrev_b32_e32 v205, 2, v219
	s_waitcnt lgkmcnt(0)
	v_mfma_f32_32x32x16_bf16 v[20:35], v[54:57], v[116:119], v[20:35]
	ds_read_b128 v[54:57], v246 offset:2048
	s_waitcnt lgkmcnt(0)
	v_mfma_f32_32x32x16_bf16 v[36:51], v[54:57], v[120:123], v[36:51]
	ds_read_b128 v[54:57], v246 offset:2560
	s_waitcnt lgkmcnt(0)
	v_mfma_f32_32x32x16_bf16 v[20:35], v[54:57], v[120:123], v[20:35]
	ds_read_b128 v[54:57], v246 offset:4096
	s_waitcnt lgkmcnt(0)
	v_mfma_f32_32x32x16_bf16 v[36:51], v[54:57], v[124:127], v[36:51]
	ds_read_b128 v[54:57], v246 offset:4608
	s_waitcnt lgkmcnt(0)
	v_mfma_f32_32x32x16_bf16 v[20:35], v[54:57], v[124:127], v[20:35]
	ds_read_b128 v[54:57], v246 offset:6144
	s_waitcnt lgkmcnt(0)
	v_mfma_f32_32x32x16_bf16 v[36:51], v[54:57], v[128:131], v[36:51]
	ds_read_b128 v[54:57], v246 offset:6656
	s_waitcnt lgkmcnt(0)
	v_mfma_f32_32x32x16_bf16 v[20:35], v[54:57], v[128:131], v[20:35]
	s_nop 15
	s_nop 7
	s_cbranch_scc1 .LBB0_881
	s_lshl_b32 s0, s51, 6
	v_subrev_u32_e32 v2, s0, v205
	v_add_u32_e32 v54, 0x120, v2
	v_add_u32_e32 v53, 0x100, v2
	v_cmp_le_i32_e32 vcc, v54, v204
	s_nop 5
	v_cndmask_b32_e32 v20, v232, v20, vcc
	v_cmp_lt_i32_e32 vcc, v53, v204
	s_nop 1
	v_cndmask_b32_e32 v37, v232, v37, vcc
	v_cmp_le_i32_e32 vcc, v53, v204
	v_add_u32_e32 v53, 0x121, v2
	s_nop 0
	v_cndmask_b32_e32 v36, v232, v36, vcc
	v_cmp_le_i32_e32 vcc, v53, v204
	v_add_u32_e32 v53, 0x102, v2
	s_nop 0
	v_cndmask_b32_e32 v21, v232, v21, vcc
	v_cmp_le_i32_e32 vcc, v53, v204
	v_add_u32_e32 v53, 0x122, v2
	s_nop 0
	v_cndmask_b32_e32 v38, v232, v38, vcc
	v_cmp_le_i32_e32 vcc, v53, v204
	v_add_u32_e32 v53, 0x103, v2
	s_nop 0
	v_cndmask_b32_e32 v22, v232, v22, vcc
	v_cmp_le_i32_e32 vcc, v53, v204
	v_add_u32_e32 v53, 0x123, v2
	s_nop 0
	v_cndmask_b32_e32 v39, v232, v39, vcc
	v_cmp_le_i32_e32 vcc, v53, v204
	v_add_u32_e32 v53, 0x108, v2
	s_nop 0
	v_cndmask_b32_e32 v23, v232, v23, vcc
	v_cmp_le_i32_e32 vcc, v53, v204
	v_add_u32_e32 v53, 0x128, v2
	s_nop 0
	v_cndmask_b32_e32 v40, v232, v40, vcc
	v_cmp_le_i32_e32 vcc, v53, v204
	v_add_u32_e32 v53, 0x109, v2
	s_nop 0
	v_cndmask_b32_e32 v24, v232, v24, vcc
	v_cmp_le_i32_e32 vcc, v53, v204
	v_add_u32_e32 v53, 0x129, v2
	s_nop 0
	v_cndmask_b32_e32 v41, v232, v41, vcc
	v_cmp_le_i32_e32 vcc, v53, v204
	v_add_u32_e32 v53, 0x10a, v2
	s_nop 0
	v_cndmask_b32_e32 v25, v232, v25, vcc
	v_cmp_le_i32_e32 vcc, v53, v204
	v_add_u32_e32 v53, 0x12a, v2
	s_nop 0
	v_cndmask_b32_e32 v42, v232, v42, vcc
	v_cmp_le_i32_e32 vcc, v53, v204
	v_add_u32_e32 v53, 0x10b, v2
	s_nop 0
	v_cndmask_b32_e32 v26, v232, v26, vcc
	v_cmp_le_i32_e32 vcc, v53, v204
	v_add_u32_e32 v53, 0x12b, v2
	s_nop 0
	v_cndmask_b32_e32 v43, v232, v43, vcc
	v_cmp_le_i32_e32 vcc, v53, v204
	v_add_u32_e32 v53, 0x110, v2
	s_nop 0
	v_cndmask_b32_e32 v27, v232, v27, vcc
	v_cmp_le_i32_e32 vcc, v53, v204
	v_add_u32_e32 v53, 0x130, v2
	s_nop 0
	v_cndmask_b32_e32 v44, v232, v44, vcc
	v_cmp_le_i32_e32 vcc, v53, v204
	v_add_u32_e32 v53, 0x111, v2
	s_nop 0
	v_cndmask_b32_e32 v28, v232, v28, vcc
	v_cmp_le_i32_e32 vcc, v53, v204
	v_add_u32_e32 v53, 0x131, v2
	s_nop 0
	v_cndmask_b32_e32 v45, v232, v45, vcc
	v_cmp_le_i32_e32 vcc, v53, v204
	v_add_u32_e32 v53, 0x112, v2
	s_nop 0
	v_cndmask_b32_e32 v29, v232, v29, vcc
	v_cmp_le_i32_e32 vcc, v53, v204
	v_add_u32_e32 v53, 0x132, v2
	s_nop 0
	v_cndmask_b32_e32 v46, v232, v46, vcc
	v_cmp_le_i32_e32 vcc, v53, v204
	v_add_u32_e32 v53, 0x113, v2
	s_nop 0
	v_cndmask_b32_e32 v30, v232, v30, vcc
	v_cmp_le_i32_e32 vcc, v53, v204
	v_add_u32_e32 v53, 0x133, v2
	s_nop 0
	v_cndmask_b32_e32 v47, v232, v47, vcc
	v_cmp_le_i32_e32 vcc, v53, v204
	v_add_u32_e32 v53, 0x118, v2
	s_nop 0
	v_cndmask_b32_e32 v31, v232, v31, vcc
	v_cmp_le_i32_e32 vcc, v53, v204
	v_add_u32_e32 v53, 0x138, v2
	s_nop 0
	v_cndmask_b32_e32 v48, v232, v48, vcc
	v_cmp_le_i32_e32 vcc, v53, v204
	v_add_u32_e32 v53, 0x119, v2
	s_nop 0
	v_cndmask_b32_e32 v32, v232, v32, vcc
	v_cmp_le_i32_e32 vcc, v53, v204
	v_add_u32_e32 v53, 0x139, v2
	s_nop 0
	v_cndmask_b32_e32 v49, v232, v49, vcc
	v_cmp_le_i32_e32 vcc, v53, v204
	v_add_u32_e32 v53, 0x11a, v2
	s_nop 0
	v_cndmask_b32_e32 v33, v232, v33, vcc
	v_cmp_le_i32_e32 vcc, v53, v204
	v_add_u32_e32 v53, 0x13a, v2
	s_nop 0
	v_cndmask_b32_e32 v50, v232, v50, vcc
	v_cmp_le_i32_e32 vcc, v53, v204
	v_add_u32_e32 v53, 0x11b, v2
	v_add_u32_e32 v2, 0x13b, v2
	v_cndmask_b32_e32 v34, v232, v34, vcc
	v_cmp_le_i32_e32 vcc, v53, v204
	s_nop 1
	v_cndmask_b32_e32 v51, v232, v51, vcc
	v_cmp_le_i32_e32 vcc, v2, v204
	s_nop 1
	v_cndmask_b32_e32 v35, v232, v35, vcc

.LBB0_883:
	s_add_u32 s26, s50, s26
	s_addc_u32 s27, s49, s27
	s_lshl_b32 s22, s45, 4
	v_lshrrev_b32_e32 v2, 2, v1
	v_and_or_b32 v220, s22, 48, v2
	s_ashr_i32 s22, s28, 3
	s_andn2_b32 s22, s22, 31
	s_and_b32 s29, s28, 0x3fffffc0
	s_ashr_i32 s23, s22, 31
	s_cmp_lg_u32 0, -1
	s_cselect_b32 s30, 0, 0
	s_add_i32 s49, s46, s30
	v_lshlrev_b32_e32 v224, 3, v52
	v_lshlrev_b32_e32 v53, 1, v52
	v_lshlrev_b32_e32 v52, 4, v52
	s_add_u32 s4, s26, s4
	v_lshlrev_b32_e32 v2, 10, v220
	v_and_b32_e32 v52, 0xc0, v52
	s_addc_u32 s5, s27, s5
	v_and_b32_e32 v222, 24, v224
	v_and_b32_e32 v223, 32, v53
	v_lshl_or_b32 v221, v219, 8, v52
	v_lshl_add_u64 v[52:53], s[4:5], 0, v[2:3]
	v_lshl_add_u64 v[52:53], s[22:23], 1, v[52:53]
	v_lshlrev_b32_e32 v2, 1, v222
	v_lshl_add_u64 v[208:209], v[52:53], 0, v[2:3]
	v_max3_f32 v52, v36, v37, v20
	v_max3_f32 v53, v38, v39, v21
	v_add_u32_e32 v54, 0, v223
	v_max3_f32 v52, v52, v22, v23
	v_max3_f32 v53, v53, v42, v43
	v_add3_u32 v247, v54, v222, v221
	v_max3_f32 v52, v52, v40, v41
	v_max3_f32 v53, v53, v26, v27
	v_lshl_add_u64 v[210:211], v[206:207], 0, s[54:55]
	v_max3_f32 v52, v52, v24, v25
	v_max3_f32 v53, v53, v46, v47
	s_lshl_b32 s26, s29, 2
	v_max3_f32 v52, v52, v44, v45
	v_max3_f32 v53, v53, v30, v31
	s_mov_b32 s25, 1
	v_max3_f32 v52, v52, v28, v29
	v_max3_f32 v53, v53, v50, v51
	s_mov_b32 s28, 0
	v_max3_f32 v52, v52, v48, v49
	v_max3_f32 v53, v53, v34, v35
	s_add_i32 s48, s26, 0
	v_max3_f32 v52, v52, v32, v33
	s_add_i32 s50, s49, 0x6000
	v_max_f32_e32 v52, v52, v53
	s_and_b64 vcc, exec, s[0:1]
	v_mov_b32_e32 v53, v52
	s_nop 1
	v_permlane32_swap_b32_e32 v52, v53
	v_max_f32_e32 v52, v52, v53
	s_nop 0
	v_max_f32_e32 v52, v52, v228
	s_nop 0
	v_add_f32_e32 v225, v3, v52
	v_sub_f32_e32 v53, v36, v52
	v_sub_f32_e32 v54, v37, v52
	v_sub_f32_e32 v55, v38, v52
	v_sub_f32_e32 v56, v39, v52
	v_sub_f32_e32 v57, v40, v52
	s_nop 0
	v_xor_b32_e32 v36, 0x80000000, v225
	v_sub_f32_e32 v58, v41, v52
	v_sub_f32_e32 v59, v42, v52
	v_sub_f32_e32 v60, v43, v52
	v_sub_f32_e32 v61, v44, v52
	v_sub_f32_e32 v62, v45, v52
	v_sub_f32_e32 v63, v46, v52
	v_sub_f32_e32 v64, v47, v52
	v_sub_f32_e32 v65, v48, v52
	v_sub_f32_e32 v66, v49, v52
	v_sub_f32_e32 v67, v50, v52
	v_sub_f32_e32 v83, v51, v52
	v_mov_b32_e32 v37, v36
	v_mov_b32_e32 v38, v36
	v_mov_b32_e32 v39, v36
	v_mov_b32_e32 v40, v36
	v_mov_b32_e32 v41, v36
	v_mov_b32_e32 v42, v36
	v_mov_b32_e32 v43, v36
	v_mov_b32_e32 v44, v36
	v_mov_b32_e32 v45, v36
	v_mov_b32_e32 v46, v36
	v_mov_b32_e32 v47, v36
	v_mov_b32_e32 v48, v36
	v_mov_b32_e32 v49, v36
	v_mov_b32_e32 v50, v36
	v_mov_b32_e32 v51, v36
	s_waitcnt vmcnt(0) lgkmcnt(0)
	s_barrier
	s_mov_b32 m0, s49
	s_nop 0
	global_load_lds_dwordx4 v[210:211], off
	s_mov_b64 s[4:5], 0x10000
	v_lshl_add_u64 v[212:213], v[208:209], 0, s[4:5]
	s_add_i32 s4, s49, 0x8000
	s_mov_b32 m0, s4
	s_nop 0
	global_load_lds_dwordx4 v[212:213], off
	ds_read_b128 v[176:179], v246 offset:8192
	ds_read_b128 v[168:171], v246 offset:8704
	ds_read_b128 v[172:175], v246 offset:10240
	ds_read_b128 v[164:167], v246 offset:10752
	ds_read_b128 v[160:163], v246 offset:12288
	ds_read_b128 v[156:159], v246 offset:12800
	ds_read_b128 v[152:155], v246 offset:14336
	ds_read_b128 v[148:151], v246 offset:14848
	v_sub_f32_e32 v20, v20, v52
	v_sub_f32_e32 v21, v21, v52
	v_sub_f32_e32 v22, v22, v52
	v_sub_f32_e32 v23, v23, v52
	v_sub_f32_e32 v24, v24, v52
	v_sub_f32_e32 v25, v25, v52
	v_sub_f32_e32 v26, v26, v52
	v_sub_f32_e32 v27, v27, v52
	v_sub_f32_e32 v28, v28, v52
	v_sub_f32_e32 v29, v29, v52
	v_sub_f32_e32 v30, v30, v52
	v_sub_f32_e32 v31, v31, v52
	v_sub_f32_e32 v32, v32, v52
	v_sub_f32_e32 v33, v33, v52
	v_sub_f32_e32 v34, v34, v52
	v_sub_f32_e32 v35, v35, v52
	v_exp_f32_e32 v68, v53
	v_exp_f32_e32 v69, v54
	v_exp_f32_e32 v70, v55
	v_exp_f32_e32 v71, v56
	v_exp_f32_e32 v72, v57
	v_exp_f32_e32 v73, v58
	v_exp_f32_e32 v74, v59
	v_exp_f32_e32 v75, v60
	v_exp_f32_e32 v76, v61
	v_exp_f32_e32 v77, v62
	v_exp_f32_e32 v78, v63
	v_exp_f32_e32 v79, v64
	v_exp_f32_e32 v80, v65
	v_exp_f32_e32 v81, v66
	v_exp_f32_e32 v82, v67
	v_exp_f32_e32 v83, v83
	v_exp_f32_e32 v52, v20
	v_exp_f32_e32 v53, v21
	v_exp_f32_e32 v54, v22
	v_exp_f32_e32 v55, v23
	v_exp_f32_e32 v56, v24
	v_exp_f32_e32 v57, v25
	v_exp_f32_e32 v58, v26
	v_exp_f32_e32 v59, v27
	v_exp_f32_e32 v60, v28
	v_exp_f32_e32 v61, v29
	v_exp_f32_e32 v62, v30
	v_exp_f32_e32 v63, v31
	v_exp_f32_e32 v64, v32
	v_exp_f32_e32 v65, v33
	v_exp_f32_e32 v66, v34
	v_exp_f32_e32 v67, v35
	s_waitcnt vmcnt(2) lgkmcnt(0)
	s_barrier
	v_cmp_gt_u32_e64 s[4:5], 32, v1
	s_cbranch_vccnz .LBB0_899
	v_mov_b32_e32 v20, 0x60
	s_mov_b64 s[0:1], 0x50000
	v_lshl_or_b32 v250, v219, 2, v20
	v_mov_b64_e32 v[34:35], v[18:19]
	v_lshl_add_u32 v245, v218, 2, s48
	v_lshl_add_u32 v249, v219, 4, s48
	v_lshl_add_u64 v[214:215], v[208:209], 0, s[54:55]
	v_lshl_add_u64 v[216:217], v[206:207], 0, s[0:1]
	v_mov_b32_e32 v248, 0
	s_mov_b32 s25, 0
	s_movk_i32 s29, 0x2000
	s_movk_i32 s0, 0x4000
	s_mov_b32 s28, -1
	v_mov_b64_e32 v[32:33], v[16:17]
	v_mov_b64_e32 v[30:31], v[14:15]
	v_mov_b64_e32 v[28:29], v[12:13]
	v_mov_b64_e32 v[26:27], v[10:11]
	v_mov_b64_e32 v[24:25], v[8:9]
	v_mov_b64_e32 v[22:23], v[6:7]
	v_mov_b64_e32 v[20:21], v[4:5]
.LBB0_885:
	s_mov_b32 s1, s25
	s_mov_b32 s25, s0
	v_add_u32_e32 v184, s1, v247
	ds_read_b64_tr_b16 v[180:181], v184 offset:24576
	ds_read_b64_tr_b16 v[182:183], v184 offset:25088
	v_add_f32_e32 v84, v68, v69
	v_add_f32_e32 v84, v70, v84
	v_add_f32_e32 v84, v71, v84
	v_add_f32_e32 v84, v72, v84
	v_add_f32_e32 v100, v73, v84
	v_mfma_f32_32x32x16_bf16 v[84:99], v[176:179], v[116:119], v[36:51]
	v_cvt_pk_bf16_f32 v144, v68, v69
	v_cvt_pk_bf16_f32 v145, v70, v71
	ds_read_b64_tr_b16 v[176:177], v184 offset:28672
	ds_read_b64_tr_b16 v[178:179], v184 offset:29184
	v_add_f32_e32 v68, v74, v100
	v_add_f32_e32 v68, v75, v68
	v_add_f32_e32 v68, v76, v68
	v_add_f32_e32 v68, v77, v68
	v_cvt_pk_bf16_f32 v146, v72, v73
	v_cvt_pk_bf16_f32 v147, v74, v75
	v_mfma_f32_32x32x16_bf16 v[100:115], v[168:171], v[116:119], v[36:51]
	ds_read_b64_tr_b16 v[168:169], v184 offset:25600
	ds_read_b64_tr_b16 v[170:171], v184 offset:26112
	v_mfma_f32_32x32x16_bf16 v[84:99], v[172:175], v[120:123], v[84:99]
	v_add_f32_e32 v68, v78, v68
	v_add_f32_e32 v68, v79, v68
	v_add_f32_e32 v68, v80, v68
	v_add_f32_e32 v68, v81, v68
	v_cvt_pk_bf16_f32 v140, v76, v77
	v_cvt_pk_bf16_f32 v141, v78, v79
	ds_read_b64_tr_b16 v[172:173], v184 offset:29696
	ds_read_b64_tr_b16 v[174:175], v184 offset:30208
	v_add_f32_e32 v68, v82, v68
	v_add_f32_e32 v68, v83, v68
	v_add_f32_e32 v68, v52, v68
	v_add_f32_e32 v68, v53, v68
	v_cvt_pk_bf16_f32 v142, v80, v81
	v_cvt_pk_bf16_f32 v143, v82, v83
	v_mfma_f32_32x32x16_bf16 v[100:115], v[164:167], v[120:123], v[100:115]
	ds_read_b64_tr_b16 v[164:165], v184 offset:26624
	ds_read_b64_tr_b16 v[166:167], v184 offset:27136
	v_mfma_f32_32x32x16_bf16 v[84:99], v[160:163], v[124:127], v[84:99]
	v_add_f32_e32 v68, v54, v68
	v_add_f32_e32 v68, v55, v68
	v_add_f32_e32 v68, v56, v68
	v_add_f32_e32 v68, v57, v68
	v_cvt_pk_bf16_f32 v136, v52, v53
	v_cvt_pk_bf16_f32 v137, v54, v55
	ds_read_b64_tr_b16 v[160:161], v184 offset:30720
	ds_read_b64_tr_b16 v[162:163], v184 offset:31232
	v_add_f32_e32 v52, v58, v68
	v_add_f32_e32 v52, v59, v52
	v_add_f32_e32 v52, v60, v52
	v_add_f32_e32 v52, v61, v52
	v_cvt_pk_bf16_f32 v138, v56, v57
	v_cvt_pk_bf16_f32 v139, v58, v59
	v_mfma_f32_32x32x16_bf16 v[100:115], v[156:159], v[124:127], v[100:115]
	ds_read_b64_tr_b16 v[156:157], v184 offset:27648
	ds_read_b64_tr_b16 v[158:159], v184 offset:28160
	v_mfma_f32_32x32x16_bf16 v[84:99], v[152:155], v[128:131], v[84:99]
	v_add_f32_e32 v52, v62, v52
	v_add_f32_e32 v52, v63, v52
	v_add_f32_e32 v52, v64, v52
	v_add_f32_e32 v52, v65, v52
	v_cvt_pk_bf16_f32 v132, v60, v61
	v_cvt_pk_bf16_f32 v133, v62, v63
	ds_read_b64_tr_b16 v[152:153], v184 offset:31744
	ds_read_b64_tr_b16 v[154:155], v184 offset:32256
	v_add_f32_e32 v52, v66, v52
	v_add_f32_e32 v52, v67, v52
	v_mfma_f32_32x32x16_bf16 v[100:115], v[148:151], v[128:131], v[100:115]
	v_add_f32_e32 v148, 0, v52
	v_cvt_pk_bf16_f32 v134, v64, v65
	v_cvt_pk_bf16_f32 v135, v66, v67
	s_mov_b32 s26, 0xffff0000
	s_mov_b32 s27, -1
	v_lshl_add_u64 v[52:53], v[216:217], 0, s[26:27]
	s_add_i32 s0, s29, s49
	s_mov_b32 m0, s0
	s_nop 0
	global_load_lds_dwordx4 v[52:53], off
	v_lshl_add_u64 v[52:53], v[214:215], 0, s[26:27]
	s_add_i32 s0, s25, s50
	s_mov_b32 m0, s0
	s_nop 0
	global_load_lds_dwordx4 v[52:53], off
	v_subrev_u32_e32 v53, 32, v250
	v_cmp_gt_i32_e32 vcc, v53, v204
	v_subrev_u32_e32 v54, 30, v250
	v_subrev_u32_e32 v55, 29, v250
	v_cndmask_b32_e32 v68, v232, v84, vcc
	v_cmp_gt_i32_e32 vcc, v250, v204
	v_subrev_u32_e32 v56, 24, v250
	v_subrev_u32_e32 v57, 23, v250
	v_cndmask_b32_e32 v52, v232, v100, vcc
	v_cmp_ge_i32_e32 vcc, v53, v204
	v_add_u32_e32 v53, 1, v250
	v_subrev_u32_e32 v58, 22, v250
	v_cndmask_b32_e32 v69, v232, v85, vcc
	v_cmp_gt_i32_e32 vcc, v53, v204
	v_subrev_u32_e32 v59, 21, v250
	v_add_u32_e32 v60, -16, v250
	v_cndmask_b32_e32 v53, v232, v101, vcc
	v_cmp_gt_i32_e32 vcc, v54, v204
	v_add_u32_e32 v54, 2, v250
	v_add_u32_e32 v61, -15, v250
	v_cndmask_b32_e32 v70, v232, v86, vcc
	v_cmp_gt_i32_e32 vcc, v54, v204
	v_add_u32_e32 v62, -14, v250
	v_add_u32_e32 v63, -13, v250
	v_cndmask_b32_e32 v54, v232, v102, vcc
	v_cmp_gt_i32_e32 vcc, v55, v204
	v_add_u32_e32 v55, 3, v250
	v_add_u32_e32 v64, -8, v250
	v_cndmask_b32_e32 v71, v232, v87, vcc
	v_cmp_gt_i32_e32 vcc, v55, v204
	v_add_u32_e32 v65, -7, v250
	v_max_f32_e32 v84, v69, v69
	v_cndmask_b32_e32 v55, v232, v103, vcc
	v_cmp_gt_i32_e32 vcc, v56, v204
	v_add_u32_e32 v56, 8, v250
	v_max_f32_e32 v85, v68, v68
	v_cndmask_b32_e32 v72, v232, v88, vcc
	v_cmp_gt_i32_e32 vcc, v56, v204
	v_max_f32_e32 v84, v85, v84
	v_add_u32_e32 v66, -6, v250
	v_cndmask_b32_e32 v56, v232, v104, vcc
	v_cmp_gt_i32_e32 vcc, v57, v204
	v_add_u32_e32 v57, 9, v250
	v_max3_f32 v85, v70, v71, v53
	v_cndmask_b32_e32 v73, v232, v89, vcc
	v_cmp_gt_i32_e32 vcc, v57, v204
	v_max3_f32 v84, v84, v52, v54
	v_max3_f32 v84, v84, v55, v72
	v_cndmask_b32_e32 v57, v232, v105, vcc
	v_cmp_gt_i32_e32 vcc, v58, v204
	v_add_u32_e32 v58, 10, v250
	v_add_u32_e32 v67, -5, v250
	v_cndmask_b32_e32 v74, v232, v90, vcc
	v_cmp_gt_i32_e32 vcc, v58, v204
	v_max3_f32 v84, v84, v73, v56
	v_add_f32_e32 v202, v248, v148
	v_cndmask_b32_e32 v58, v232, v106, vcc
	v_cmp_gt_i32_e32 vcc, v59, v204
	v_add_u32_e32 v59, 11, v250
	s_nop 0
	v_cndmask_b32_e32 v75, v232, v91, vcc
	v_cmp_gt_i32_e32 vcc, v59, v204
	v_max3_f32 v85, v85, v74, v75
	s_nop 0
	v_cndmask_b32_e32 v59, v232, v107, vcc
	v_cmp_gt_i32_e32 vcc, v60, v204
	v_add_u32_e32 v60, 16, v250
	v_max3_f32 v85, v85, v58, v59
	v_cndmask_b32_e32 v76, v232, v92, vcc
	v_cmp_gt_i32_e32 vcc, v60, v204
	v_max3_f32 v84, v84, v57, v76
	s_nop 0
	v_cndmask_b32_e32 v60, v232, v108, vcc
	v_cmp_gt_i32_e32 vcc, v61, v204
	v_add_u32_e32 v61, 17, v250
	s_nop 0
	v_cndmask_b32_e32 v77, v232, v93, vcc
	v_cmp_gt_i32_e32 vcc, v61, v204
	v_max3_f32 v84, v84, v77, v60
	s_nop 0
	v_cndmask_b32_e32 v61, v232, v109, vcc
	v_cmp_gt_i32_e32 vcc, v62, v204
	v_add_u32_e32 v62, 18, v250
	s_nop 0
	v_cndmask_b32_e32 v78, v232, v94, vcc
	v_cmp_gt_i32_e32 vcc, v62, v204
	s_nop 1
	v_cndmask_b32_e32 v62, v232, v110, vcc
	v_cmp_gt_i32_e32 vcc, v63, v204
	v_add_u32_e32 v63, 19, v250
	s_nop 0
	v_cndmask_b32_e32 v79, v232, v95, vcc
	v_cmp_gt_i32_e32 vcc, v63, v204
	v_max3_f32 v85, v85, v78, v79
	s_nop 0
	v_cndmask_b32_e32 v63, v232, v111, vcc
	v_cmp_gt_i32_e32 vcc, v64, v204
	v_add_u32_e32 v64, 24, v250
	v_max3_f32 v85, v85, v62, v63
	v_cndmask_b32_e32 v80, v232, v96, vcc
	v_cmp_gt_i32_e32 vcc, v64, v204
	v_max3_f32 v84, v84, v61, v80
	s_nop 0
	v_cndmask_b32_e32 v64, v232, v112, vcc
	v_cmp_gt_i32_e32 vcc, v65, v204
	v_add_u32_e32 v65, 25, v250
	s_nop 0
	v_cndmask_b32_e32 v81, v232, v97, vcc
	v_cmp_gt_i32_e32 vcc, v65, v204
	v_max3_f32 v84, v84, v81, v64
	s_nop 0
	v_cndmask_b32_e32 v65, v232, v113, vcc
	v_cmp_gt_i32_e32 vcc, v66, v204
	v_add_u32_e32 v66, 26, v250
	s_nop 0
	v_cndmask_b32_e32 v82, v232, v98, vcc
	v_cmp_gt_i32_e32 vcc, v66, v204
	s_nop 1
	v_cndmask_b32_e32 v66, v232, v114, vcc
	v_cmp_gt_i32_e32 vcc, v67, v204
	v_add_u32_e32 v67, 27, v250
	s_nop 0
	v_cndmask_b32_e32 v83, v232, v99, vcc
	v_cmp_gt_i32_e32 vcc, v67, v204
	v_max3_f32 v85, v85, v82, v83
	s_nop 0
	v_cndmask_b32_e32 v67, v232, v115, vcc
	v_max3_f32 v85, v85, v66, v67
	v_max3_f32 v84, v84, v65, v85
	v_mov_b32_e32 v85, v84
	s_nop 1
	v_permlane32_swap_b32_e32 v84, v85
	v_max_f32_e32 v85, v85, v85
	v_max_f32_e32 v84, v84, v84
	v_max_f32_e32 v84, v84, v85
	v_cmp_lt_f32_e32 vcc, s33, v84
	s_cmp_lg_u64 vcc, 0
	s_cselect_b64 s[0:1], -1, 0
	s_cbranch_vccnz .LBB0_893

.LBB0_888:
	s_add_i32 s0, s25, 0x2000
	s_cmpk_lg_i32 s25, 0x4000
	s_cselect_b32 s30, s0, 0
	v_add_u32_e32 v194, s29, v247
	ds_read_b64_tr_b16 v[160:161], v194 offset:24576
	ds_read_b64_tr_b16 v[162:163], v194 offset:25088
	v_add_f32_e32 v84, v68, v69
	v_add_f32_e32 v84, v70, v84
	v_add_f32_e32 v84, v71, v84
	v_add_f32_e32 v84, v72, v84
	v_add_f32_e32 v104, v73, v84
	v_mfma_f32_32x32x16_bf16 v[84:99], v[100:103], v[116:119], v[36:51]
	v_cvt_pk_bf16_f32 v144, v68, v69
	v_cvt_pk_bf16_f32 v145, v70, v71
	ds_read_b64_tr_b16 v[156:157], v194 offset:28672
	ds_read_b64_tr_b16 v[158:159], v194 offset:29184
	v_add_f32_e32 v68, v74, v104
	v_add_f32_e32 v68, v75, v68
	v_add_f32_e32 v68, v76, v68
	v_add_f32_e32 v68, v77, v68
	v_cvt_pk_bf16_f32 v146, v72, v73
	v_cvt_pk_bf16_f32 v147, v74, v75
	v_mfma_f32_32x32x16_bf16 v[100:115], v[148:151], v[116:119], v[36:51]
	ds_read_b64_tr_b16 v[148:149], v194 offset:25600
	ds_read_b64_tr_b16 v[150:151], v194 offset:26112
	v_mfma_f32_32x32x16_bf16 v[84:99], v[184:187], v[120:123], v[84:99]
	v_add_f32_e32 v68, v78, v68
	v_add_f32_e32 v68, v79, v68
	v_add_f32_e32 v68, v80, v68
	v_add_f32_e32 v68, v81, v68
	v_cvt_pk_bf16_f32 v140, v76, v77
	v_cvt_pk_bf16_f32 v141, v78, v79
	ds_read_b64_tr_b16 v[152:153], v194 offset:29696
	ds_read_b64_tr_b16 v[154:155], v194 offset:30208
	v_add_f32_e32 v68, v82, v68
	v_add_f32_e32 v68, v83, v68
	v_add_f32_e32 v68, v52, v68
	v_add_f32_e32 v68, v53, v68
	v_cvt_pk_bf16_f32 v142, v80, v81
	v_cvt_pk_bf16_f32 v143, v82, v83
	v_mfma_f32_32x32x16_bf16 v[100:115], v[180:183], v[120:123], v[100:115]
	ds_read_b64_tr_b16 v[180:181], v194 offset:26624
	ds_read_b64_tr_b16 v[182:183], v194 offset:27136
	v_mfma_f32_32x32x16_bf16 v[84:99], v[176:179], v[124:127], v[84:99]
	v_add_f32_e32 v68, v54, v68
	v_add_f32_e32 v68, v55, v68
	v_add_f32_e32 v68, v56, v68
	v_add_f32_e32 v68, v57, v68
	v_cvt_pk_bf16_f32 v136, v52, v53
	v_cvt_pk_bf16_f32 v137, v54, v55
	ds_read_b64_tr_b16 v[184:185], v194 offset:30720
	ds_read_b64_tr_b16 v[186:187], v194 offset:31232
	v_add_f32_e32 v52, v58, v68
	v_add_f32_e32 v52, v59, v52
	v_add_f32_e32 v52, v60, v52
	v_add_f32_e32 v52, v61, v52
	v_cvt_pk_bf16_f32 v138, v56, v57
	v_cvt_pk_bf16_f32 v139, v58, v59
	v_mfma_f32_32x32x16_bf16 v[100:115], v[172:175], v[124:127], v[100:115]
	ds_read_b64_tr_b16 v[188:189], v194 offset:27648
	ds_read_b64_tr_b16 v[190:191], v194 offset:28160
	v_mfma_f32_32x32x16_bf16 v[84:99], v[168:171], v[128:131], v[84:99]
	v_add_f32_e32 v52, v62, v52
	v_add_f32_e32 v52, v63, v52
	v_add_f32_e32 v52, v64, v52
	v_add_f32_e32 v52, v65, v52
	v_cvt_pk_bf16_f32 v132, v60, v61
	v_cvt_pk_bf16_f32 v133, v62, v63
	ds_read_b64_tr_b16 v[192:193], v194 offset:31744
	ds_read_b64_tr_b16 v[194:195], v194 offset:32256
	v_add_f32_e32 v52, v66, v52
	v_add_f32_e32 v52, v67, v52
	v_mfma_f32_32x32x16_bf16 v[100:115], v[164:167], v[128:131], v[100:115]
	v_add_f32_e32 v164, 0, v52
	v_cvt_pk_bf16_f32 v134, v64, v65
	v_cvt_pk_bf16_f32 v135, v66, v67
	v_add_u32_e32 v53, 32, v250
	v_cmp_gt_i32_e32 vcc, v53, v204
	v_add_u32_e32 v52, 64, v250
	v_add_u32_e32 v54, 34, v250
	v_cndmask_b32_e32 v68, v232, v84, vcc
	v_cmp_gt_i32_e32 vcc, v52, v204
	v_add_u32_e32 v55, 35, v250
	v_add_u32_e32 v56, 40, v250
	s_nop 0
	v_cndmask_b32_e32 v52, v232, v100, vcc
	v_cmp_ge_i32_e32 vcc, v53, v204
	v_add_u32_e32 v53, 0x41, v250
	v_add_u32_e32 v57, 41, v250
	v_cndmask_b32_e32 v69, v232, v85, vcc
	v_cmp_gt_i32_e32 vcc, v53, v204
	v_add_u32_e32 v58, 42, v250
	v_add_u32_e32 v59, 43, v250
	v_cndmask_b32_e32 v53, v232, v101, vcc
	v_cmp_gt_i32_e32 vcc, v54, v204
	v_add_u32_e32 v54, 0x42, v250
	v_add_u32_e32 v60, 48, v250
	v_cndmask_b32_e32 v70, v232, v86, vcc
	v_cmp_gt_i32_e32 vcc, v54, v204
	v_add_u32_e32 v61, 49, v250
	v_add_u32_e32 v62, 50, v250
	v_cndmask_b32_e32 v54, v232, v102, vcc
	v_cmp_gt_i32_e32 vcc, v55, v204
	v_add_u32_e32 v55, 0x43, v250
	v_add_u32_e32 v63, 51, v250
	v_cndmask_b32_e32 v71, v232, v87, vcc
	v_cmp_gt_i32_e32 vcc, v55, v204
	v_add_u32_e32 v64, 56, v250
	v_add_u32_e32 v65, 57, v250
	v_cndmask_b32_e32 v55, v232, v103, vcc
	v_cmp_gt_i32_e32 vcc, v56, v204
	v_add_u32_e32 v56, 0x48, v250
	v_max_f32_e32 v84, v69, v69
	v_cndmask_b32_e32 v72, v232, v88, vcc
	v_cmp_gt_i32_e32 vcc, v56, v204
	v_max_f32_e32 v85, v68, v68
	v_max_f32_e32 v84, v85, v84
	v_cndmask_b32_e32 v56, v232, v104, vcc
	v_cmp_gt_i32_e32 vcc, v57, v204
	v_add_u32_e32 v57, 0x49, v250
	v_add_u32_e32 v66, 58, v250
	v_cndmask_b32_e32 v73, v232, v89, vcc
	v_cmp_gt_i32_e32 vcc, v57, v204
	v_max3_f32 v85, v70, v71, v53
	v_max3_f32 v84, v84, v52, v54
	v_cndmask_b32_e32 v57, v232, v105, vcc
	v_cmp_gt_i32_e32 vcc, v58, v204
	v_add_u32_e32 v58, 0x4a, v250
	v_max3_f32 v84, v84, v55, v72
	v_cndmask_b32_e32 v74, v232, v90, vcc
	v_cmp_gt_i32_e32 vcc, v58, v204
	v_add_u32_e32 v67, 59, v250
	v_max3_f32 v84, v84, v73, v56
	v_cndmask_b32_e32 v58, v232, v106, vcc
	v_cmp_gt_i32_e32 vcc, v59, v204
	v_add_u32_e32 v59, 0x4b, v250
	s_add_i32 s0, s25, s49
	v_cndmask_b32_e32 v75, v232, v91, vcc
	v_cmp_gt_i32_e32 vcc, v59, v204
	v_max3_f32 v85, v85, v74, v75
	s_mov_b32 m0, s0
	s_nop 0
	global_load_lds_dwordx4 v[216:217], off
	s_add_i32 s0, s30, s50
	v_cndmask_b32_e32 v59, v232, v107, vcc
	v_cmp_gt_i32_e32 vcc, v60, v204
	v_add_u32_e32 v60, 0x50, v250
	v_max3_f32 v85, v85, v58, v59
	v_cndmask_b32_e32 v76, v232, v92, vcc
	v_cmp_gt_i32_e32 vcc, v60, v204
	v_max3_f32 v84, v84, v57, v76
	s_mov_b32 m0, s0
	s_nop 0
	global_load_lds_dwordx4 v[214:215], off
	v_add_f32_e32 v248, v202, v164
	v_cndmask_b32_e32 v60, v232, v108, vcc
	v_cmp_gt_i32_e32 vcc, v61, v204
	v_add_u32_e32 v61, 0x51, v250
	s_nop 0
	v_cndmask_b32_e32 v77, v232, v93, vcc
	v_cmp_gt_i32_e32 vcc, v61, v204
	v_max3_f32 v84, v84, v77, v60
	s_nop 0
	v_cndmask_b32_e32 v61, v232, v109, vcc
	v_cmp_gt_i32_e32 vcc, v62, v204
	v_add_u32_e32 v62, 0x52, v250
	s_nop 0
	v_cndmask_b32_e32 v78, v232, v94, vcc
	v_cmp_gt_i32_e32 vcc, v62, v204
	s_nop 1
	v_cndmask_b32_e32 v62, v232, v110, vcc
	v_cmp_gt_i32_e32 vcc, v63, v204
	v_add_u32_e32 v63, 0x53, v250
	s_nop 0
	v_cndmask_b32_e32 v79, v232, v95, vcc
	v_cmp_gt_i32_e32 vcc, v63, v204
	v_max3_f32 v85, v85, v78, v79
	s_nop 0
	v_cndmask_b32_e32 v63, v232, v111, vcc
	v_cmp_gt_i32_e32 vcc, v64, v204
	v_add_u32_e32 v64, 0x58, v250
	v_max3_f32 v85, v85, v62, v63
	v_cndmask_b32_e32 v80, v232, v96, vcc
	v_cmp_gt_i32_e32 vcc, v64, v204
	v_max3_f32 v84, v84, v61, v80
	s_nop 0
	v_cndmask_b32_e32 v64, v232, v112, vcc
	v_cmp_gt_i32_e32 vcc, v65, v204
	v_add_u32_e32 v65, 0x59, v250
	s_nop 0
	v_cndmask_b32_e32 v81, v232, v97, vcc
	v_cmp_gt_i32_e32 vcc, v65, v204
	v_max3_f32 v84, v84, v81, v64
	s_nop 0
	v_cndmask_b32_e32 v65, v232, v113, vcc
	v_cmp_gt_i32_e32 vcc, v66, v204
	v_add_u32_e32 v66, 0x5a, v250
	s_nop 0
	v_cndmask_b32_e32 v82, v232, v98, vcc
	v_cmp_gt_i32_e32 vcc, v66, v204
	s_nop 1
	v_cndmask_b32_e32 v66, v232, v114, vcc
	v_cmp_gt_i32_e32 vcc, v67, v204
	v_add_u32_e32 v67, 0x5b, v250
	s_nop 0
	v_cndmask_b32_e32 v83, v232, v99, vcc
	v_cmp_gt_i32_e32 vcc, v67, v204
	v_max3_f32 v85, v85, v82, v83
	s_nop 0
	v_cndmask_b32_e32 v67, v232, v115, vcc
	v_max3_f32 v85, v85, v66, v67
	v_max3_f32 v84, v84, v65, v85
	v_mov_b32_e32 v85, v84
	s_nop 1
	v_permlane32_swap_b32_e32 v84, v85
	v_max_f32_e32 v85, v85, v85
	v_max_f32_e32 v84, v84, v84
	v_max_f32_e32 v84, v84, v85
	v_cmp_lt_f32_e32 vcc, s33, v84
	s_cmp_lg_u64 vcc, 0
	s_cselect_b64 s[0:1], -1, 0
	s_cbranch_vccnz .LBB0_896

.LBB0_903:
	v_add_u32_e32 v184, s28, v247
	ds_read_b64_tr_b16 v[180:181], v184 offset:24576
	ds_read_b64_tr_b16 v[182:183], v184 offset:25088
	v_mfma_f32_32x32x16_bf16 v[100:115], v[176:179], v[116:119], v[36:51]
	v_add_f32_e32 v84, v68, v69
	v_add_f32_e32 v84, v70, v84
	v_add_f32_e32 v84, v71, v84
	v_add_f32_e32 v84, v72, v84
	v_add_f32_e32 v84, v73, v84
	v_cvt_pk_bf16_f32 v144, v68, v69
	v_cvt_pk_bf16_f32 v145, v70, v71
	ds_read_b64_tr_b16 v[176:177], v184 offset:28672
	ds_read_b64_tr_b16 v[178:179], v184 offset:29184
	v_add_f32_e32 v68, v74, v84
	v_mfma_f32_32x32x16_bf16 v[84:99], v[168:171], v[116:119], v[36:51]
	v_add_f32_e32 v68, v75, v68
	v_add_f32_e32 v68, v76, v68
	v_add_f32_e32 v132, v77, v68
	v_cvt_pk_bf16_f32 v146, v72, v73
	v_cvt_pk_bf16_f32 v147, v74, v75
	ds_read_b64_tr_b16 v[68:69], v184 offset:25600
	ds_read_b64_tr_b16 v[70:71], v184 offset:26112
	v_mfma_f32_32x32x16_bf16 v[100:115], v[172:175], v[120:123], v[100:115]
	v_add_f32_e32 v72, v78, v132
	v_add_f32_e32 v72, v79, v72
	v_add_f32_e32 v72, v80, v72
	v_add_f32_e32 v132, v81, v72
	v_cvt_pk_bf16_f32 v140, v76, v77
	v_cvt_pk_bf16_f32 v141, v78, v79
	ds_read_b64_tr_b16 v[72:73], v184 offset:29696
	ds_read_b64_tr_b16 v[74:75], v184 offset:30208
	v_mfma_f32_32x32x16_bf16 v[84:99], v[164:167], v[120:123], v[84:99]
	v_add_f32_e32 v76, v82, v132
	v_add_f32_e32 v76, v83, v76
	v_add_f32_e32 v76, v52, v76
	v_add_f32_e32 v132, v53, v76
	v_cvt_pk_bf16_f32 v142, v80, v81
	v_cvt_pk_bf16_f32 v143, v82, v83
	ds_read_b64_tr_b16 v[76:77], v184 offset:26624
	ds_read_b64_tr_b16 v[78:79], v184 offset:27136
	v_mfma_f32_32x32x16_bf16 v[100:115], v[160:163], v[124:127], v[100:115]
	v_add_f32_e32 v80, v54, v132
	v_add_f32_e32 v80, v55, v80
	v_add_f32_e32 v80, v56, v80
	v_add_f32_e32 v80, v57, v80
	v_cvt_pk_bf16_f32 v136, v52, v53
	v_cvt_pk_bf16_f32 v137, v54, v55
	ds_read_b64_tr_b16 v[52:53], v184 offset:30720
	ds_read_b64_tr_b16 v[54:55], v184 offset:31232
	v_mfma_f32_32x32x16_bf16 v[84:99], v[156:159], v[124:127], v[84:99]
	v_add_f32_e32 v80, v58, v80
	v_add_f32_e32 v80, v59, v80
	v_add_f32_e32 v80, v60, v80
	v_add_f32_e32 v80, v61, v80
	v_cvt_pk_bf16_f32 v138, v56, v57
	v_cvt_pk_bf16_f32 v139, v58, v59
	ds_read_b64_tr_b16 v[56:57], v184 offset:27648
	ds_read_b64_tr_b16 v[58:59], v184 offset:28160
	v_mfma_f32_32x32x16_bf16 v[100:115], v[152:155], v[128:131], v[100:115]
	v_add_f32_e32 v80, v62, v80
	v_add_f32_e32 v80, v63, v80
	v_add_f32_e32 v80, v64, v80
	v_add_f32_e32 v80, v65, v80
	v_cvt_pk_bf16_f32 v132, v60, v61
	v_cvt_pk_bf16_f32 v133, v62, v63
	ds_read_b64_tr_b16 v[60:61], v184 offset:31744
	ds_read_b64_tr_b16 v[62:63], v184 offset:32256
	v_mfma_f32_32x32x16_bf16 v[84:99], v[148:151], v[128:131], v[84:99]
	v_add_f32_e32 v80, v66, v80
	v_add_f32_e32 v80, v67, v80
	v_cvt_pk_bf16_f32 v134, v64, v65
	v_cvt_pk_bf16_f32 v135, v66, v67
	s_add_i32 s1, s0, 1
	s_cmp_ge_i32 s1, s51
	s_cselect_b64 s[24:25], -1, 0
	s_and_b64 vcc, exec, s[24:25]
	s_cbranch_vccnz .LBB0_905
	s_add_i32 s1, s53, s49
	s_mov_b32 m0, s1
	s_nop 0
	global_load_lds_dwordx4 v[210:211], off
.LBB0_905:
	s_add_i32 s1, s54, s50
	s_mov_b32 m0, s1
	s_nop 0
	global_load_lds_dwordx4 v[194:195], off
	s_add_i32 s30, s56, s0
	s_add_i32 s1, s30, -2
	s_cmp_lt_i32 s1, 0
	s_cbranch_scc1 .LBB0_907
	v_add_u32_e32 v64, s52, v205
	v_add_u32_e32 v65, 32, v64
	v_cmp_le_i32_e32 vcc, v65, v204
	v_add_u32_e32 v65, 33, v64
	s_nop 0
	v_cndmask_b32_e32 v84, v232, v84, vcc
	v_cmp_lt_i32_e32 vcc, v64, v204
	s_nop 1
	v_cndmask_b32_e32 v101, v232, v101, vcc
	v_cmp_le_i32_e32 vcc, v64, v204
	s_nop 1
	v_cndmask_b32_e32 v100, v232, v100, vcc
	v_cmp_le_i32_e32 vcc, v65, v204
	v_add_u32_e32 v65, 2, v64
	s_nop 0
	v_cndmask_b32_e32 v85, v232, v85, vcc
	v_cmp_le_i32_e32 vcc, v65, v204
	v_add_u32_e32 v65, 34, v64
	s_nop 0
	v_cndmask_b32_e32 v102, v232, v102, vcc
	v_cmp_le_i32_e32 vcc, v65, v204
	v_add_u32_e32 v65, 3, v64
	s_nop 0
	v_cndmask_b32_e32 v86, v232, v86, vcc
	v_cmp_le_i32_e32 vcc, v65, v204
	v_add_u32_e32 v65, 35, v64
	s_nop 0
	v_cndmask_b32_e32 v103, v232, v103, vcc
	v_cmp_le_i32_e32 vcc, v65, v204
	v_add_u32_e32 v65, 8, v64
	s_nop 0
	v_cndmask_b32_e32 v87, v232, v87, vcc
	v_cmp_le_i32_e32 vcc, v65, v204
	v_add_u32_e32 v65, 40, v64
	s_nop 0
	v_cndmask_b32_e32 v104, v232, v104, vcc
	v_cmp_le_i32_e32 vcc, v65, v204
	v_add_u32_e32 v65, 9, v64
	s_nop 0
	v_cndmask_b32_e32 v88, v232, v88, vcc
	v_cmp_le_i32_e32 vcc, v65, v204
	v_add_u32_e32 v65, 41, v64
	s_nop 0
	v_cndmask_b32_e32 v105, v232, v105, vcc
	v_cmp_le_i32_e32 vcc, v65, v204
	v_add_u32_e32 v65, 10, v64
	s_nop 0
	v_cndmask_b32_e32 v89, v232, v89, vcc
	v_cmp_le_i32_e32 vcc, v65, v204
	v_add_u32_e32 v65, 42, v64
	s_nop 0
	v_cndmask_b32_e32 v106, v232, v106, vcc
	v_cmp_le_i32_e32 vcc, v65, v204
	v_add_u32_e32 v65, 11, v64
	s_nop 0
	v_cndmask_b32_e32 v90, v232, v90, vcc
	v_cmp_le_i32_e32 vcc, v65, v204
	v_add_u32_e32 v65, 43, v64
	s_nop 0
	v_cndmask_b32_e32 v107, v232, v107, vcc
	v_cmp_le_i32_e32 vcc, v65, v204
	v_add_u32_e32 v65, 16, v64
	s_nop 0
	v_cndmask_b32_e32 v91, v232, v91, vcc
	v_cmp_le_i32_e32 vcc, v65, v204
	v_add_u32_e32 v65, 48, v64
	s_nop 0
	v_cndmask_b32_e32 v108, v232, v108, vcc
	v_cmp_le_i32_e32 vcc, v65, v204
	v_add_u32_e32 v65, 17, v64
	s_nop 0
	v_cndmask_b32_e32 v92, v232, v92, vcc
	v_cmp_le_i32_e32 vcc, v65, v204
	v_add_u32_e32 v65, 49, v64
	s_nop 0
	v_cndmask_b32_e32 v109, v232, v109, vcc
	v_cmp_le_i32_e32 vcc, v65, v204
	v_add_u32_e32 v65, 18, v64
	s_nop 0
	v_cndmask_b32_e32 v93, v232, v93, vcc
	v_cmp_le_i32_e32 vcc, v65, v204
	v_add_u32_e32 v65, 50, v64
	s_nop 0
	v_cndmask_b32_e32 v110, v232, v110, vcc
	v_cmp_le_i32_e32 vcc, v65, v204
	v_add_u32_e32 v65, 19, v64
	s_nop 0
	v_cndmask_b32_e32 v94, v232, v94, vcc
	v_cmp_le_i32_e32 vcc, v65, v204
	v_add_u32_e32 v65, 51, v64
	s_nop 0
	v_cndmask_b32_e32 v111, v232, v111, vcc
	v_cmp_le_i32_e32 vcc, v65, v204
	v_add_u32_e32 v65, 24, v64
	s_nop 0
	v_cndmask_b32_e32 v95, v232, v95, vcc
	v_cmp_le_i32_e32 vcc, v65, v204
	v_add_u32_e32 v65, 56, v64
	s_nop 0
	v_cndmask_b32_e32 v112, v232, v112, vcc
	v_cmp_le_i32_e32 vcc, v65, v204
	v_add_u32_e32 v65, 25, v64
	s_nop 0
	v_cndmask_b32_e32 v96, v232, v96, vcc
	v_cmp_le_i32_e32 vcc, v65, v204
	v_add_u32_e32 v65, 57, v64
	s_nop 0
	v_cndmask_b32_e32 v113, v232, v113, vcc
	v_cmp_le_i32_e32 vcc, v65, v204
	v_add_u32_e32 v65, 26, v64
	s_nop 0
	v_cndmask_b32_e32 v97, v232, v97, vcc
	v_cmp_le_i32_e32 vcc, v65, v204
	v_add_u32_e32 v65, 58, v64
	s_nop 0
	v_cndmask_b32_e32 v114, v232, v114, vcc
	v_cmp_le_i32_e32 vcc, v65, v204
	v_add_u32_e32 v65, 27, v64
	v_add_u32_e32 v64, 59, v64
	v_cndmask_b32_e32 v98, v232, v98, vcc
	v_cmp_le_i32_e32 vcc, v65, v204
	s_nop 1
	v_cndmask_b32_e32 v115, v232, v115, vcc
	v_cmp_le_i32_e32 vcc, v64, v204
	s_nop 1
	v_cndmask_b32_e32 v99, v232, v99, vcc

.LBB0_912:
	v_add_u32_e32 v196, s53, v247
	ds_read_b64_tr_b16 v[188:189], v196 offset:24576
	ds_read_b64_tr_b16 v[190:191], v196 offset:25088
	v_mfma_f32_32x32x16_bf16 v[68:83], v[176:179], v[116:119], v[36:51]
	v_add_f32_e32 v52, v100, v101
	v_add_f32_e32 v52, v102, v52
	v_add_f32_e32 v52, v103, v52
	v_add_f32_e32 v52, v104, v52
	v_add_f32_e32 v52, v105, v52
	v_cvt_pk_bf16_f32 v144, v100, v101
	v_cvt_pk_bf16_f32 v145, v102, v103
	ds_read_b64_tr_b16 v[184:185], v196 offset:28672
	ds_read_b64_tr_b16 v[186:187], v196 offset:29184
	v_add_f32_e32 v52, v106, v52
	v_add_f32_e32 v52, v107, v52
	v_add_f32_e32 v52, v108, v52
	v_add_f32_e32 v100, v109, v52
	v_mfma_f32_32x32x16_bf16 v[52:67], v[168:171], v[116:119], v[36:51]
	v_cvt_pk_bf16_f32 v146, v104, v105
	v_cvt_pk_bf16_f32 v147, v106, v107
	ds_read_b64_tr_b16 v[180:181], v196 offset:25600
	ds_read_b64_tr_b16 v[182:183], v196 offset:26112
	v_mfma_f32_32x32x16_bf16 v[68:83], v[172:175], v[120:123], v[68:83]
	v_add_f32_e32 v100, v110, v100
	v_add_f32_e32 v100, v111, v100
	v_add_f32_e32 v100, v112, v100
	v_add_f32_e32 v100, v113, v100
	v_cvt_pk_bf16_f32 v140, v108, v109
	v_cvt_pk_bf16_f32 v141, v110, v111
	ds_read_b64_tr_b16 v[108:109], v196 offset:29696
	ds_read_b64_tr_b16 v[110:111], v196 offset:30208
	v_mfma_f32_32x32x16_bf16 v[52:67], v[164:167], v[120:123], v[52:67]
	v_add_f32_e32 v100, v114, v100
	v_add_f32_e32 v100, v115, v100
	v_add_f32_e32 v100, v84, v100
	v_add_f32_e32 v100, v85, v100
	v_cvt_pk_bf16_f32 v142, v112, v113
	v_cvt_pk_bf16_f32 v143, v114, v115
	ds_read_b64_tr_b16 v[104:105], v196 offset:26624
	ds_read_b64_tr_b16 v[106:107], v196 offset:27136
	v_mfma_f32_32x32x16_bf16 v[68:83], v[160:163], v[124:127], v[68:83]
	v_add_f32_e32 v100, v86, v100
	v_add_f32_e32 v100, v87, v100
	v_add_f32_e32 v100, v88, v100
	v_add_f32_e32 v112, v89, v100
	v_cvt_pk_bf16_f32 v136, v84, v85
	v_cvt_pk_bf16_f32 v137, v86, v87
	ds_read_b64_tr_b16 v[100:101], v196 offset:30720
	ds_read_b64_tr_b16 v[102:103], v196 offset:31232
	v_mfma_f32_32x32x16_bf16 v[52:67], v[156:159], v[124:127], v[52:67]
	v_add_f32_e32 v84, v90, v112
	v_add_f32_e32 v84, v91, v84
	v_add_f32_e32 v84, v92, v84
	v_add_f32_e32 v84, v93, v84
	v_cvt_pk_bf16_f32 v138, v88, v89
	v_cvt_pk_bf16_f32 v139, v90, v91
	ds_read_b64_tr_b16 v[88:89], v196 offset:27648
	ds_read_b64_tr_b16 v[90:91], v196 offset:28160
	v_mfma_f32_32x32x16_bf16 v[68:83], v[152:155], v[128:131], v[68:83]
	v_add_f32_e32 v84, v94, v84
	v_add_f32_e32 v84, v95, v84
	v_add_f32_e32 v84, v96, v84
	v_add_f32_e32 v112, v97, v84
	v_cvt_pk_bf16_f32 v132, v92, v93
	v_cvt_pk_bf16_f32 v133, v94, v95
	ds_read_b64_tr_b16 v[84:85], v196 offset:31744
	ds_read_b64_tr_b16 v[86:87], v196 offset:32256
	v_mfma_f32_32x32x16_bf16 v[52:67], v[148:151], v[128:131], v[52:67]
	v_add_f32_e32 v92, v98, v112
	v_add_f32_e32 v92, v99, v92
	v_cvt_pk_bf16_f32 v134, v96, v97
	v_cvt_pk_bf16_f32 v135, v98, v99
	s_add_i32 s26, s0, 2
	s_cmp_ge_i32 s26, s51
	s_cselect_b64 s[28:29], -1, 0
	s_and_b64 vcc, exec, s[28:29]
	s_cbranch_vccnz .LBB0_914
	s_ashr_i32 s27, s26, 31
	s_lshl_b64 s[34:35], s[26:27], 16
	s_add_i32 s1, s54, s49
	v_lshl_add_u64 v[94:95], v[206:207], 0, s[34:35]
	s_mov_b32 m0, s1
	s_nop 0
	global_load_lds_dwordx4 v[94:95], off
.LBB0_914:
	s_add_i32 s1, s54, 0x2000
	s_cmpk_lg_i32 s54, 0x4000
	s_cselect_b32 s53, s1, 0
	s_cmp_lt_i32 s0, s51
	s_cselect_b64 s[34:35], -1, 0
	s_cmp_ge_i32 s0, s51
	s_cbranch_scc1 .LBB0_916
	s_ashr_i32 s1, s0, 31
	s_lshl_b64 s[0:1], s[0:1], 16
	s_add_i32 s27, s53, s50
	v_lshl_add_u64 v[94:95], v[208:209], 0, s[0:1]
	s_mov_b32 m0, s27
	s_nop 0
	global_load_lds_dwordx4 v[94:95], off

.LBB0_953:
	v_add_u32_e32 v188, s28, v247
	ds_read_b64_tr_b16 v[180:181], v188 offset:24576
	ds_read_b64_tr_b16 v[182:183], v188 offset:25088
	v_mfma_f32_32x32x16_bf16 v[100:115], v[176:179], v[116:119], v[36:51]
	v_add_f32_e32 v84, v68, v69
	v_add_f32_e32 v84, v70, v84
	v_add_f32_e32 v84, v71, v84
	v_add_f32_e32 v84, v72, v84
	v_add_f32_e32 v84, v73, v84
	v_cvt_pk_bf16_f32 v144, v68, v69
	v_cvt_pk_bf16_f32 v145, v70, v71
	ds_read_b64_tr_b16 v[176:177], v188 offset:28672
	ds_read_b64_tr_b16 v[178:179], v188 offset:29184
	v_add_f32_e32 v68, v74, v84
	v_mfma_f32_32x32x16_bf16 v[84:99], v[168:171], v[116:119], v[36:51]
	v_add_f32_e32 v68, v75, v68
	v_add_f32_e32 v68, v76, v68
	v_add_f32_e32 v132, v77, v68
	v_cvt_pk_bf16_f32 v146, v72, v73
	v_cvt_pk_bf16_f32 v147, v74, v75
	ds_read_b64_tr_b16 v[68:69], v188 offset:25600
	ds_read_b64_tr_b16 v[70:71], v188 offset:26112
	v_mfma_f32_32x32x16_bf16 v[100:115], v[172:175], v[120:123], v[100:115]
	v_add_f32_e32 v72, v78, v132
	v_add_f32_e32 v72, v79, v72
	v_add_f32_e32 v72, v80, v72
	v_add_f32_e32 v132, v81, v72
	v_cvt_pk_bf16_f32 v140, v76, v77
	v_cvt_pk_bf16_f32 v141, v78, v79
	ds_read_b64_tr_b16 v[72:73], v188 offset:29696
	ds_read_b64_tr_b16 v[74:75], v188 offset:30208
	v_mfma_f32_32x32x16_bf16 v[84:99], v[164:167], v[120:123], v[84:99]
	v_add_f32_e32 v76, v82, v132
	v_add_f32_e32 v76, v83, v76
	v_add_f32_e32 v76, v52, v76
	v_add_f32_e32 v132, v53, v76
	v_cvt_pk_bf16_f32 v142, v80, v81
	v_cvt_pk_bf16_f32 v143, v82, v83
	ds_read_b64_tr_b16 v[76:77], v188 offset:26624
	ds_read_b64_tr_b16 v[78:79], v188 offset:27136
	v_mfma_f32_32x32x16_bf16 v[100:115], v[160:163], v[124:127], v[100:115]
	v_add_f32_e32 v80, v54, v132
	v_add_f32_e32 v80, v55, v80
	v_add_f32_e32 v80, v56, v80
	v_add_f32_e32 v80, v57, v80
	v_cvt_pk_bf16_f32 v136, v52, v53
	v_cvt_pk_bf16_f32 v137, v54, v55
	ds_read_b64_tr_b16 v[52:53], v188 offset:30720
	ds_read_b64_tr_b16 v[54:55], v188 offset:31232
	v_mfma_f32_32x32x16_bf16 v[84:99], v[156:159], v[124:127], v[84:99]
	v_add_f32_e32 v80, v58, v80
	v_add_f32_e32 v80, v59, v80
	v_add_f32_e32 v80, v60, v80
	v_add_f32_e32 v80, v61, v80
	v_cvt_pk_bf16_f32 v138, v56, v57
	v_cvt_pk_bf16_f32 v139, v58, v59
	ds_read_b64_tr_b16 v[56:57], v188 offset:27648
	ds_read_b64_tr_b16 v[58:59], v188 offset:28160
	v_mfma_f32_32x32x16_bf16 v[100:115], v[152:155], v[128:131], v[100:115]
	v_add_f32_e32 v80, v62, v80
	v_add_f32_e32 v80, v63, v80
	v_add_f32_e32 v80, v64, v80
	v_add_f32_e32 v80, v65, v80
	v_cvt_pk_bf16_f32 v132, v60, v61
	v_cvt_pk_bf16_f32 v133, v62, v63
	ds_read_b64_tr_b16 v[60:61], v188 offset:31744
	ds_read_b64_tr_b16 v[62:63], v188 offset:32256
	v_mfma_f32_32x32x16_bf16 v[84:99], v[148:151], v[128:131], v[84:99]
	v_add_f32_e32 v80, v66, v80
	v_add_f32_e32 v80, v67, v80
	v_cvt_pk_bf16_f32 v134, v64, v65
	v_cvt_pk_bf16_f32 v135, v66, v67
	v_lshl_add_u64 v[188:189], v[184:185], 0, s[0:1]
	v_lshl_add_u64 v[64:65], v[188:189], 0, s[54:55]
	s_add_i32 s26, s31, s49
	s_mov_b32 m0, s26
	s_nop 0
	global_load_lds_dwordx4 v[64:65], off
	v_lshl_add_u64 v[190:191], v[186:187], 0, s[0:1]
	s_mov_b64 s[26:27], 0x10000
	v_lshl_add_u64 v[64:65], v[190:191], 0, s[26:27]
	s_add_i32 s26, s30, s50
	s_mov_b32 m0, s26
	s_nop 0
	global_load_lds_dwordx4 v[64:65], off
	v_add_f32_e32 v195, v248, v80

.LBB0_956:
	s_add_i32 s26, s30, 0x2000
	s_cmpk_lg_i32 s30, 0x4000
	s_cselect_b32 s53, s26, 0
	v_add_u32_e32 v196, s31, v247
	ds_read_b64_tr_b16 v[152:153], v196 offset:24576
	ds_read_b64_tr_b16 v[154:155], v196 offset:25088
	v_mfma_f32_32x32x16_bf16 v[68:83], v[64:67], v[116:119], v[36:51]
	v_add_f32_e32 v52, v100, v101
	v_add_f32_e32 v52, v102, v52
	v_add_f32_e32 v52, v103, v52
	v_add_f32_e32 v52, v104, v52
	v_add_f32_e32 v52, v105, v52
	v_cvt_pk_bf16_f32 v144, v100, v101
	v_cvt_pk_bf16_f32 v145, v102, v103
	ds_read_b64_tr_b16 v[148:149], v196 offset:28672
	ds_read_b64_tr_b16 v[150:151], v196 offset:29184
	v_add_f32_e32 v52, v106, v52
	v_add_f32_e32 v52, v107, v52
	v_add_f32_e32 v52, v108, v52
	v_add_f32_e32 v132, v109, v52
	v_mfma_f32_32x32x16_bf16 v[52:67], v[176:179], v[116:119], v[36:51]
	v_cvt_pk_bf16_f32 v146, v104, v105
	v_cvt_pk_bf16_f32 v147, v106, v107
	ds_read_b64_tr_b16 v[100:101], v196 offset:25600
	ds_read_b64_tr_b16 v[102:103], v196 offset:26112
	v_mfma_f32_32x32x16_bf16 v[68:83], v[180:183], v[120:123], v[68:83]
	v_add_f32_e32 v104, v110, v132
	v_add_f32_e32 v104, v111, v104
	v_add_f32_e32 v104, v112, v104
	v_add_f32_e32 v132, v113, v104
	v_cvt_pk_bf16_f32 v140, v108, v109
	v_cvt_pk_bf16_f32 v141, v110, v111
	ds_read_b64_tr_b16 v[104:105], v196 offset:29696
	ds_read_b64_tr_b16 v[106:107], v196 offset:30208
	v_mfma_f32_32x32x16_bf16 v[52:67], v[172:175], v[120:123], v[52:67]
	v_add_f32_e32 v108, v114, v132
	v_add_f32_e32 v108, v115, v108
	v_add_f32_e32 v108, v84, v108
	v_add_f32_e32 v132, v85, v108
	v_cvt_pk_bf16_f32 v142, v112, v113
	v_cvt_pk_bf16_f32 v143, v114, v115
	ds_read_b64_tr_b16 v[108:109], v196 offset:26624
	ds_read_b64_tr_b16 v[110:111], v196 offset:27136
	v_mfma_f32_32x32x16_bf16 v[68:83], v[168:171], v[124:127], v[68:83]
	v_add_f32_e32 v112, v86, v132
	v_add_f32_e32 v112, v87, v112
	v_add_f32_e32 v112, v88, v112
	v_add_f32_e32 v112, v89, v112
	v_cvt_pk_bf16_f32 v136, v84, v85
	v_cvt_pk_bf16_f32 v137, v86, v87
	ds_read_b64_tr_b16 v[84:85], v196 offset:30720
	ds_read_b64_tr_b16 v[86:87], v196 offset:31232
	v_mfma_f32_32x32x16_bf16 v[52:67], v[164:167], v[124:127], v[52:67]
	v_add_f32_e32 v112, v90, v112
	v_add_f32_e32 v112, v91, v112
	v_add_f32_e32 v112, v92, v112
	v_add_f32_e32 v112, v93, v112
	v_cvt_pk_bf16_f32 v138, v88, v89
	v_cvt_pk_bf16_f32 v139, v90, v91
	ds_read_b64_tr_b16 v[88:89], v196 offset:27648
	ds_read_b64_tr_b16 v[90:91], v196 offset:28160
	v_mfma_f32_32x32x16_bf16 v[68:83], v[160:163], v[128:131], v[68:83]
	v_add_f32_e32 v112, v94, v112
	v_add_f32_e32 v112, v95, v112
	v_add_f32_e32 v112, v96, v112
	v_add_f32_e32 v112, v97, v112
	v_cvt_pk_bf16_f32 v132, v92, v93
	v_cvt_pk_bf16_f32 v133, v94, v95
	ds_read_b64_tr_b16 v[92:93], v196 offset:31744
	ds_read_b64_tr_b16 v[94:95], v196 offset:32256
	v_mfma_f32_32x32x16_bf16 v[52:67], v[156:159], v[128:131], v[52:67]
	v_add_f32_e32 v112, v98, v112
	v_add_f32_e32 v112, v99, v112
	v_cvt_pk_bf16_f32 v134, v96, v97
	v_cvt_pk_bf16_f32 v135, v98, v99
	v_lshl_add_u64 v[96:97], v[188:189], 0, s[80:81]
	s_add_i32 s26, s30, s49
	s_mov_b32 m0, s26
	s_nop 0
	global_load_lds_dwordx4 v[96:97], off
	s_mov_b64 s[26:27], 0x20000
	v_lshl_add_u64 v[96:97], v[190:191], 0, s[26:27]
	s_add_i32 s26, s53, s50
	s_mov_b32 m0, s26
	s_nop 0
	global_load_lds_dwordx4 v[96:97], off
	v_add_f32_e32 v248, v195, v112

.LBB0_968:
	v_add_u32_e32 v180, s54, v247
	ds_read_b64_tr_b16 v[104:105], v180 offset:24576
	ds_read_b64_tr_b16 v[106:107], v180 offset:25088
	v_add_f32_e32 v84, v68, v69
	v_add_f32_e32 v84, v70, v84
	v_add_f32_e32 v84, v71, v84
	v_add_f32_e32 v84, v72, v84
	v_add_f32_e32 v108, v73, v84
	v_mfma_f32_32x32x16_bf16 v[84:99], v[176:179], v[116:119], v[36:51]
	v_cvt_pk_bf16_f32 v144, v68, v69
	v_cvt_pk_bf16_f32 v145, v70, v71
	ds_read_b64_tr_b16 v[100:101], v180 offset:28672
	ds_read_b64_tr_b16 v[102:103], v180 offset:29184
	v_mfma_f32_32x32x16_bf16 v[36:51], v[168:171], v[116:119], v[36:51]
	v_add_f32_e32 v68, v74, v108
	v_add_f32_e32 v68, v75, v68
	v_add_f32_e32 v68, v76, v68
	v_add_f32_e32 v68, v77, v68
	v_cvt_pk_bf16_f32 v146, v72, v73
	v_cvt_pk_bf16_f32 v147, v74, v75
	ds_read_b64_tr_b16 v[108:109], v180 offset:25600
	ds_read_b64_tr_b16 v[110:111], v180 offset:26112
	v_mfma_f32_32x32x16_bf16 v[84:99], v[172:175], v[120:123], v[84:99]
	v_add_f32_e32 v68, v78, v68
	v_add_f32_e32 v68, v79, v68
	v_add_f32_e32 v68, v80, v68
	v_add_f32_e32 v68, v81, v68
	v_cvt_pk_bf16_f32 v140, v76, v77
	v_cvt_pk_bf16_f32 v141, v78, v79
	ds_read_b64_tr_b16 v[112:113], v180 offset:29696
	ds_read_b64_tr_b16 v[114:115], v180 offset:30208
	v_mfma_f32_32x32x16_bf16 v[36:51], v[164:167], v[120:123], v[36:51]
	v_add_f32_e32 v68, v82, v68
	v_add_f32_e32 v68, v83, v68
	v_add_f32_e32 v68, v52, v68
	v_add_f32_e32 v68, v53, v68
	v_cvt_pk_bf16_f32 v142, v80, v81
	v_cvt_pk_bf16_f32 v143, v82, v83
	ds_read_b64_tr_b16 v[164:165], v180 offset:26624
	ds_read_b64_tr_b16 v[166:167], v180 offset:27136
	v_mfma_f32_32x32x16_bf16 v[84:99], v[160:163], v[124:127], v[84:99]
	v_add_f32_e32 v68, v54, v68
	v_add_f32_e32 v68, v55, v68
	v_add_f32_e32 v68, v56, v68
	v_add_f32_e32 v68, v57, v68
	v_cvt_pk_bf16_f32 v136, v52, v53
	v_cvt_pk_bf16_f32 v137, v54, v55
	ds_read_b64_tr_b16 v[160:161], v180 offset:30720
	ds_read_b64_tr_b16 v[162:163], v180 offset:31232
	v_mfma_f32_32x32x16_bf16 v[36:51], v[156:159], v[124:127], v[36:51]
	v_add_f32_e32 v52, v58, v68
	v_add_f32_e32 v52, v59, v52
	v_add_f32_e32 v52, v60, v52
	v_add_f32_e32 v52, v61, v52
	v_cvt_pk_bf16_f32 v138, v56, v57
	v_cvt_pk_bf16_f32 v139, v58, v59
	ds_read_b64_tr_b16 v[156:157], v180 offset:27648
	ds_read_b64_tr_b16 v[158:159], v180 offset:28160
	v_mfma_f32_32x32x16_bf16 v[84:99], v[152:155], v[128:131], v[84:99]
	v_add_f32_e32 v52, v62, v52
	v_add_f32_e32 v52, v63, v52
	v_add_f32_e32 v52, v64, v52
	v_add_f32_e32 v52, v65, v52
	v_cvt_pk_bf16_f32 v132, v60, v61
	v_cvt_pk_bf16_f32 v133, v62, v63
	ds_read_b64_tr_b16 v[152:153], v180 offset:31744
	ds_read_b64_tr_b16 v[154:155], v180 offset:32256
	v_mfma_f32_32x32x16_bf16 v[36:51], v[148:151], v[128:131], v[36:51]
	v_add_f32_e32 v52, v66, v52
	v_add_f32_e32 v52, v67, v52
	v_add_f32_e32 v68, 0, v52
	v_cvt_pk_bf16_f32 v134, v64, v65
	v_cvt_pk_bf16_f32 v135, v66, v67
	v_or_b32_e32 v53, 0xe0, v205
	v_or_b32_e32 v52, 0xc0, v205
	v_cmp_le_i32_e32 vcc, v53, v204
	v_or_b32_e32 v54, 0xe1, v205
	v_or_b32_e32 v55, 0xe2, v205
	s_nop 1
	v_cndmask_b32_e32 v36, v232, v36, vcc
	v_cmp_lt_i32_e32 vcc, v52, v204
	v_or_b32_e32 v56, 0xe3, v205
	v_or_b32_e32 v57, 0xe8, v205
	v_cndmask_b32_e32 v53, v232, v85, vcc
	v_cmp_le_i32_e32 vcc, v52, v204
	v_or_b32_e32 v58, 0xe9, v205
	v_or_b32_e32 v59, 0xea, v205
	v_cndmask_b32_e32 v52, v232, v84, vcc
	v_cmp_le_i32_e32 vcc, v54, v204
	v_or_b32_e32 v54, 0xc2, v205
	v_or_b32_e32 v60, 0xeb, v205
	v_cndmask_b32_e32 v37, v232, v37, vcc
	v_cmp_le_i32_e32 vcc, v54, v204
	v_or_b32_e32 v61, 0xf0, v205
	v_or_b32_e32 v62, 0xf1, v205
	v_cndmask_b32_e32 v54, v232, v86, vcc
	v_cmp_le_i32_e32 vcc, v55, v204
	v_or_b32_e32 v55, 0xc3, v205
	v_or_b32_e32 v63, 0xf2, v205
	v_cndmask_b32_e32 v38, v232, v38, vcc
	v_cmp_le_i32_e32 vcc, v55, v204
	v_or_b32_e32 v64, 0xf3, v205
	v_or_b32_e32 v65, 0xf8, v205
	v_cndmask_b32_e32 v55, v232, v87, vcc
	v_cmp_le_i32_e32 vcc, v56, v204
	v_or_b32_e32 v56, 0xc8, v205
	v_or_b32_e32 v66, 0xf9, v205
	v_cndmask_b32_e32 v39, v232, v39, vcc
	v_cmp_le_i32_e32 vcc, v56, v204
	v_or_b32_e32 v67, 0xfa, v205
	v_or_b32_e32 v69, 0xfb, v205
	v_cndmask_b32_e32 v56, v232, v88, vcc
	v_cmp_le_i32_e32 vcc, v57, v204
	v_or_b32_e32 v57, 0xc9, v205
	v_max_f32_e32 v70, v52, v52
	v_cndmask_b32_e32 v40, v232, v40, vcc
	v_cmp_le_i32_e32 vcc, v57, v204
	v_add_f32_e32 v86, v248, v68
	s_nop 0
	v_cndmask_b32_e32 v57, v232, v89, vcc
	v_cmp_le_i32_e32 vcc, v58, v204
	v_or_b32_e32 v58, 0xca, v205
	s_nop 0
	v_cndmask_b32_e32 v41, v232, v41, vcc
	v_cmp_le_i32_e32 vcc, v58, v204
	s_nop 1
	v_cndmask_b32_e32 v58, v232, v90, vcc
	v_cmp_le_i32_e32 vcc, v59, v204
	v_or_b32_e32 v59, 0xcb, v205
	s_nop 0
	v_cndmask_b32_e32 v42, v232, v42, vcc
	v_cmp_le_i32_e32 vcc, v59, v204
	s_nop 1
	v_cndmask_b32_e32 v59, v232, v91, vcc
	v_cmp_le_i32_e32 vcc, v60, v204
	v_or_b32_e32 v60, 0xd0, v205
	s_nop 0
	v_cndmask_b32_e32 v43, v232, v43, vcc
	v_cmp_le_i32_e32 vcc, v60, v204
	s_nop 1
	v_cndmask_b32_e32 v60, v232, v92, vcc
	v_cmp_le_i32_e32 vcc, v61, v204
	v_or_b32_e32 v61, 0xd1, v205
	s_nop 0
	v_cndmask_b32_e32 v44, v232, v44, vcc
	v_cmp_le_i32_e32 vcc, v61, v204
	s_nop 1
	v_cndmask_b32_e32 v61, v232, v93, vcc
	v_cmp_le_i32_e32 vcc, v62, v204
	v_or_b32_e32 v62, 0xd2, v205
	s_nop 0
	v_cndmask_b32_e32 v45, v232, v45, vcc
	v_cmp_le_i32_e32 vcc, v62, v204
	s_nop 1
	v_cndmask_b32_e32 v62, v232, v94, vcc
	v_cmp_le_i32_e32 vcc, v63, v204
	v_or_b32_e32 v63, 0xd3, v205
	s_nop 0
	v_cndmask_b32_e32 v46, v232, v46, vcc
	v_cmp_le_i32_e32 vcc, v63, v204
	s_nop 1
	v_cndmask_b32_e32 v63, v232, v95, vcc
	v_cmp_le_i32_e32 vcc, v64, v204
	v_or_b32_e32 v64, 0xd8, v205
	s_nop 0
	v_cndmask_b32_e32 v47, v232, v47, vcc
	v_cmp_le_i32_e32 vcc, v64, v204
	s_nop 1
	v_cndmask_b32_e32 v64, v232, v96, vcc
	v_cmp_le_i32_e32 vcc, v65, v204
	v_or_b32_e32 v65, 0xd9, v205
	s_nop 0
	v_cndmask_b32_e32 v48, v232, v48, vcc
	v_cmp_le_i32_e32 vcc, v65, v204
	s_nop 1
	v_cndmask_b32_e32 v65, v232, v97, vcc
	v_cmp_le_i32_e32 vcc, v66, v204
	v_or_b32_e32 v66, 0xda, v205
	s_nop 0
	v_cndmask_b32_e32 v49, v232, v49, vcc
	v_cmp_le_i32_e32 vcc, v66, v204
	s_nop 1
	v_cndmask_b32_e32 v66, v232, v98, vcc
	v_cmp_le_i32_e32 vcc, v67, v204
	v_or_b32_e32 v67, 0xdb, v205
	s_nop 0
	v_cndmask_b32_e32 v50, v232, v50, vcc
	v_cmp_le_i32_e32 vcc, v67, v204
	s_nop 1
	v_cndmask_b32_e32 v67, v232, v99, vcc
	v_cmp_le_i32_e32 vcc, v69, v204
	v_max_f32_e32 v69, v53, v53
	v_max_f32_e32 v69, v70, v69
	v_max3_f32 v70, v54, v55, v37
	v_max3_f32 v69, v69, v36, v38
	v_max3_f32 v69, v69, v39, v56
	v_max3_f32 v70, v70, v58, v59
	v_max3_f32 v69, v69, v57, v40
	v_max3_f32 v70, v70, v42, v43
	v_max3_f32 v69, v69, v41, v60
	v_max3_f32 v70, v70, v62, v63
	v_max3_f32 v69, v69, v61, v44
	v_max3_f32 v70, v70, v46, v47
	v_cndmask_b32_e32 v51, v232, v51, vcc
	v_max3_f32 v69, v69, v45, v64
	v_max3_f32 v70, v70, v66, v67
	v_max3_f32 v69, v69, v65, v48
	v_max3_f32 v70, v70, v50, v51
	v_max3_f32 v68, v69, v49, v70
	v_mov_b32_e32 v69, v68
	s_nop 1
	v_permlane32_swap_b32_e32 v68, v69
	v_max_f32_e32 v69, v69, v69
	v_max_f32_e32 v68, v68, v68
	v_max_f32_e32 v68, v68, v69
	v_cmp_lt_f32_e32 vcc, s33, v68
	s_cmp_lg_u64 vcc, 0
	s_cselect_b64 s[0:1], -1, 0
	s_cbranch_vccnz .LBB0_983
	s_mov_b64 s[54:55], 0x9400380

.LBB0_976:
	s_lshl_b64 s[0:1], s[0:1], 11
	s_add_u32 s0, s42, s0
	s_addc_u32 s1, s43, s1
	s_add_u32 s0, s0, s8
	v_and_b32_e32 v89, 56, v224
	s_addc_u32 s1, s1, s9
	v_lshlrev_b32_e32 v68, 1, v89
	v_mov_b32_e32 v69, v3
	v_lshl_add_u64 v[84:85], s[0:1], 0, v[68:69]
	v_lshlrev_b32_e32 v68, 8, v1
	v_and_b32_e32 v68, 0x3800, v68
	v_lshl_add_u64 v[68:69], v[84:85], 0, v[68:69]
	s_movk_i32 s0, 0x4000
	v_add_co_u32_e64 v70, s[0:1], s0, v68
	s_cmp_lg_u32 0, -1
	s_nop 0
	v_addc_co_u32_e64 v71, s[0:1], 0, v69, s[0:1]
	s_mov_b32 s0, 0x8000
	global_load_dwordx4 v[80:83], v[68:69], off
	global_load_dwordx4 v[76:79], v[70:71], off
	v_add_co_u32_e64 v70, s[0:1], s0, v68
	v_cvt_pk_bf16_f32 v90, v52, v53
	s_nop 0
	v_addc_co_u32_e64 v71, s[0:1], 0, v69, s[0:1]
	s_mov_b32 s0, 0xc000
	s_nop 0
	v_add_co_u32_e64 v68, s[0:1], s0, v68
	v_cvt_pk_bf16_f32 v91, v54, v55
	s_nop 0
	v_addc_co_u32_e64 v69, s[0:1], 0, v69, s[0:1]
	global_load_dwordx4 v[72:75], v[70:71], off
	s_nop 0
	global_load_dwordx4 v[68:71], v[68:69], off
	s_cselect_b32 s0, 0, 0
	s_addk_i32 s0, 0x6000
	v_add3_u32 v106, v223, s0, v222
	v_cvt_pk_bf16_f32 v92, v56, v57
	v_cvt_pk_bf16_f32 v93, v58, v59
	v_cvt_pk_bf16_f32 v94, v60, v61
	v_cvt_pk_bf16_f32 v95, v62, v63
	v_cvt_pk_bf16_f32 v96, v64, v65
	v_cvt_pk_bf16_f32 v97, v66, v67
	v_cvt_pk_bf16_f32 v98, v36, v37
	v_cvt_pk_bf16_f32 v99, v38, v39
	v_cvt_pk_bf16_f32 v100, v40, v41
	v_cvt_pk_bf16_f32 v101, v42, v43
	v_cvt_pk_bf16_f32 v102, v44, v45
	v_cvt_pk_bf16_f32 v103, v46, v47
	v_cvt_pk_bf16_f32 v104, v48, v49
	v_cvt_pk_bf16_f32 v105, v50, v51
	v_add3_u32 v114, v106, v221, s53
	ds_read_b64_tr_b16 v[106:107],v114 offset:0
	ds_read_b64_tr_b16 v[108:109],v114 offset:512
	ds_read_b64_tr_b16 v[110:111],v114 offset:1024
	ds_read_b64_tr_b16 v[112:113],v114 offset:1536
	ds_read_b64_tr_b16 v[132:133],v114 offset:2048
	ds_read_b64_tr_b16 v[134:135],v114 offset:2560
	ds_read_b64_tr_b16 v[136:137],v114 offset:3072
	ds_read_b64_tr_b16 v[138:139],v114 offset:3584
	s_waitcnt lgkmcnt(0)
	s_nop 0
	v_mfma_f32_32x32x16_bf16 v[20:35], v[90:93], v[106:109], v[20:35]
	ds_read_b64_tr_b16 v[106:107],v114 offset:4096
	ds_read_b64_tr_b16 v[108:109],v114 offset:4608
	v_mfma_f32_32x32x16_bf16 v[20:35], v[94:97], v[110:113], v[20:35]
	ds_read_b64_tr_b16 v[110:111],v114 offset:5120
	ds_read_b64_tr_b16 v[112:113],v114 offset:5632
	v_mfma_f32_32x32x16_bf16 v[20:35], v[98:101], v[132:135], v[20:35]
	ds_read_b64_tr_b16 v[132:133],v114 offset:6144
	ds_read_b64_tr_b16 v[134:135],v114 offset:6656
	v_mfma_f32_32x32x16_bf16 v[20:35], v[102:105], v[136:139], v[20:35]
	ds_read_b64_tr_b16 v[136:137],v114 offset:7168
	ds_read_b64_tr_b16 v[138:139],v114 offset:7680
	s_waitcnt lgkmcnt(0)
	v_mfma_f32_32x32x16_bf16 v[4:19], v[90:93], v[106:109], v[4:19]
	s_cmp_eq_u64 s[14:15], 0
	v_mfma_f32_32x32x16_bf16 v[4:19], v[94:97], v[110:113], v[4:19]
	v_mfma_f32_32x32x16_bf16 v[4:19], v[98:101], v[132:135], v[4:19]
	v_mfma_f32_32x32x16_bf16 v[4:19], v[102:105], v[136:139], v[4:19]
	s_cbranch_scc1 .LBB0_978
	v_lshlrev_b32_e32 v90, 11, v1
	v_mov_b32_e32 v91, v3
	v_lshlrev_b32_e32 v92, 11, v220
	v_mov_b32_e32 v93, v3
	s_waitcnt lgkmcnt(0)
	s_barrier
	v_lshl_add_u64 v[90:91], s[14:15], 0, v[90:91]
	v_lshl_add_u64 v[92:93], s[16:17], 0, v[92:93]
	v_lshl_add_u64 v[90:91], s[18:19], 1, v[90:91]
	v_lshl_add_u64 v[92:93], s[22:23], 1, v[92:93]
	s_mov_b32 m0, s49
	s_nop 0
	global_load_lds_dwordx4 v[90:91], off
	v_lshl_add_u64 v[92:93], v[92:93], 0, v[2:3]
	s_mov_b32 m0, s50
	s_nop 0
	global_load_lds_dwordx4 v[92:93], off
	s_mov_b64 s[0:1], 0x20000
	s_cmp_lg_u32 0, -1
	v_lshl_add_u64 v[90:91], v[90:91], 0, s[0:1]
	s_cselect_b32 s0, 0, 0
	s_add_i32 s0, s0, s46
	s_addk_i32 s0, 0x2000
	s_mov_b32 m0, s0
	s_nop 0
	global_load_lds_dwordx4 v[90:91], off
